# tail GEMM K-loops: per-phase s_setprio toggling removed as well (all MFMA mainloops now run at static default priority)
# speedup vs baseline: 1.0181x; 1.0074x over previous
.LBB0_517:
	s_add_i32 s59, s31, 1
	s_cmp_lt_u32 s31, 3
	s_cselect_b64 s[60:61], -1, 0
	s_and_b64 s[28:29], s[60:61], exec
	s_cselect_b32 s28, s59, s30
	ds_read_b128 v[46:49], v40
	ds_read_b128 v[50:53], v40 offset:1024
	ds_read_b128 v[54:57], v40 offset:2048
	ds_read_b128 v[58:61], v40 offset:3072
	s_ashr_i32 s29, s28, 31
	s_lshl_b64 s[28:29], s[28:29], 17
	s_add_u32 s28, s84, s28
	s_addc_u32 s29, s85, s29
	s_and_b64 s[30:31], s[60:61], exec
	s_cselect_b32 s31, s29, s35
	s_cselect_b32 s30, s28, s34
	s_mov_b32 m0, s45
	ds_read_b128 v[62:65], v41
	ds_read_b128 v[66:69], v41 offset:1024
	ds_read_b128 v[70:73], v41 offset:2048
	ds_read_b128 v[74:77], v41 offset:3072
	ds_read_b128 v[78:81], v41 offset:4096
	ds_read_b128 v[82:85], v41 offset:5120
	ds_read_b128 v[86:89], v41 offset:6144
	ds_read_b128 v[90:93], v41 offset:7168
	global_load_lds_dwordx4 v[18:19], off
	s_mov_b32 m0, s46
	s_nop 0
	global_load_lds_dwordx4 v[20:21], off
	s_waitcnt lgkmcnt(8)
	s_barrier
	s_waitcnt lgkmcnt(0)
	s_waitcnt lgkmcnt(0)
	v_mfma_f32_16x16x32_bf16 v[94:97], v[46:49], v[62:65], 0
	v_mfma_f32_16x16x32_bf16 v[98:101], v[54:57], v[62:65], 0
	v_mfma_f32_16x16x32_bf16 v[102:105], v[46:49], v[70:73], 0
	v_mfma_f32_16x16x32_bf16 v[106:109], v[54:57], v[70:73], 0
	v_mfma_f32_16x16x32_bf16 v[110:113], v[46:49], v[78:81], 0
	v_mfma_f32_16x16x32_bf16 v[114:117], v[54:57], v[78:81], 0
	v_mfma_f32_16x16x32_bf16 v[118:121], v[46:49], v[86:89], 0
	v_mfma_f32_16x16x32_bf16 v[122:125], v[54:57], v[86:89], 0
	v_mfma_f32_16x16x32_bf16 v[94:97], v[50:53], v[66:69], v[94:97]
	v_mfma_f32_16x16x32_bf16 v[98:101], v[58:61], v[66:69], v[98:101]
	v_mfma_f32_16x16x32_bf16 v[102:105], v[50:53], v[74:77], v[102:105]
	v_mfma_f32_16x16x32_bf16 v[106:109], v[58:61], v[74:77], v[106:109]
	v_mfma_f32_16x16x32_bf16 v[110:113], v[50:53], v[82:85], v[110:113]
	v_mfma_f32_16x16x32_bf16 v[114:117], v[58:61], v[82:85], v[114:117]
	v_mfma_f32_16x16x32_bf16 v[118:121], v[50:53], v[90:93], v[118:121]
	v_mfma_f32_16x16x32_bf16 v[122:125], v[58:61], v[90:93], v[122:125]
	s_barrier
	v_lshl_add_u64 v[238:239], s[34:35], 0, v[2:3]
	s_mov_b32 m0, s47
	v_lshl_add_u64 v[142:143], v[238:239], 0, s[6:7]
	v_lshl_add_u64 v[240:241], s[34:35], 0, v[4:5]
	ds_read_b128 v[126:129], v42
	ds_read_b128 v[130:133], v42 offset:1024
	ds_read_b128 v[134:137], v42 offset:2048
	ds_read_b128 v[138:141], v42 offset:3072
	global_load_lds_dwordx4 v[142:143], off
	v_lshl_add_u64 v[142:143], v[240:241], 0, s[6:7]
	s_mov_b32 m0, s48
	s_nop 0
	global_load_lds_dwordx4 v[142:143], off
	s_barrier
	s_waitcnt lgkmcnt(0)
	s_waitcnt lgkmcnt(0)
	v_mfma_f32_16x16x32_bf16 v[142:145], v[126:129], v[62:65], 0
	v_mfma_f32_16x16x32_bf16 v[62:65], v[134:137], v[62:65], 0
	v_mfma_f32_16x16x32_bf16 v[142:145], v[130:133], v[66:69], v[142:145]
	v_mfma_f32_16x16x32_bf16 v[62:65], v[138:141], v[66:69], v[62:65]
	v_mfma_f32_16x16x32_bf16 v[66:69], v[126:129], v[70:73], 0
	v_mfma_f32_16x16x32_bf16 v[70:73], v[134:137], v[70:73], 0
	v_mfma_f32_16x16x32_bf16 v[66:69], v[130:133], v[74:77], v[66:69]
	v_mfma_f32_16x16x32_bf16 v[70:73], v[138:141], v[74:77], v[70:73]
	v_mfma_f32_16x16x32_bf16 v[74:77], v[126:129], v[78:81], 0
	v_mfma_f32_16x16x32_bf16 v[78:81], v[134:137], v[78:81], 0
	v_mfma_f32_16x16x32_bf16 v[74:77], v[130:133], v[82:85], v[74:77]
	v_mfma_f32_16x16x32_bf16 v[78:81], v[138:141], v[82:85], v[78:81]
	v_mfma_f32_16x16x32_bf16 v[82:85], v[126:129], v[86:89], 0
	v_mfma_f32_16x16x32_bf16 v[86:89], v[134:137], v[86:89], 0
	v_mfma_f32_16x16x32_bf16 v[82:85], v[130:133], v[90:93], v[82:85]
	v_mfma_f32_16x16x32_bf16 v[86:89], v[138:141], v[90:93], v[86:89]
	s_mov_b32 m0, s33
	s_barrier
	ds_read_b128 v[90:93], v41 offset:16384
	ds_read_b128 v[146:149], v41 offset:17408
	ds_read_b128 v[150:153], v41 offset:18432
	ds_read_b128 v[154:157], v41 offset:19456
	ds_read_b128 v[158:161], v41 offset:20480
	ds_read_b128 v[162:165], v41 offset:21504
	ds_read_b128 v[166:169], v41 offset:22528
	ds_read_b128 v[170:173], v41 offset:23552
	global_load_lds_dwordx4 v[22:23], off
	s_mov_b32 m0, s36
	s_nop 0
	global_load_lds_dwordx4 v[24:25], off
	s_barrier
	s_waitcnt lgkmcnt(0)
	s_waitcnt lgkmcnt(0)
	v_mfma_f32_16x16x32_bf16 v[174:177], v[46:49], v[90:93], 0
	v_mfma_f32_16x16x32_bf16 v[182:185], v[46:49], v[150:153], 0
	v_mfma_f32_16x16x32_bf16 v[190:193], v[46:49], v[158:161], 0
	v_mfma_f32_16x16x32_bf16 v[46:49], v[46:49], v[166:169], 0
	v_mfma_f32_16x16x32_bf16 v[174:177], v[50:53], v[146:149], v[174:177]
	v_mfma_f32_16x16x32_bf16 v[178:181], v[54:57], v[90:93], 0
	v_mfma_f32_16x16x32_bf16 v[182:185], v[50:53], v[154:157], v[182:185]
	v_mfma_f32_16x16x32_bf16 v[186:189], v[54:57], v[150:153], 0
	v_mfma_f32_16x16x32_bf16 v[190:193], v[50:53], v[162:165], v[190:193]
	v_mfma_f32_16x16x32_bf16 v[194:197], v[54:57], v[158:161], 0
	v_mfma_f32_16x16x32_bf16 v[46:49], v[50:53], v[170:173], v[46:49]
	v_mfma_f32_16x16x32_bf16 v[50:53], v[54:57], v[166:169], 0
	v_mfma_f32_16x16x32_bf16 v[178:181], v[58:61], v[146:149], v[178:181]
	v_mfma_f32_16x16x32_bf16 v[186:189], v[58:61], v[154:157], v[186:189]
	v_mfma_f32_16x16x32_bf16 v[194:197], v[58:61], v[162:165], v[194:197]
	v_mfma_f32_16x16x32_bf16 v[50:53], v[58:61], v[170:173], v[50:53]
	s_barrier
	s_add_u32 s60, s34, 0x10100
	s_addc_u32 s61, s35, 0
	s_mov_b32 m0, s49
	v_lshl_add_u64 v[54:55], s[60:61], 0, v[2:3]
	global_load_lds_dwordx4 v[54:55], off
	v_lshl_add_u64 v[54:55], s[60:61], 0, v[4:5]
	s_mov_b32 m0, s50
	s_nop 0
	global_load_lds_dwordx4 v[54:55], off
	s_waitcnt vmcnt(6)
	s_barrier
	v_mfma_f32_16x16x32_bf16 v[54:57], v[126:129], v[90:93], 0
	v_mfma_f32_16x16x32_bf16 v[58:61], v[134:137], v[90:93], 0
	v_mfma_f32_16x16x32_bf16 v[54:57], v[130:133], v[146:149], v[54:57]
	v_mfma_f32_16x16x32_bf16 v[58:61], v[138:141], v[146:149], v[58:61]
	v_mfma_f32_16x16x32_bf16 v[90:93], v[126:129], v[150:153], 0
	v_mfma_f32_16x16x32_bf16 v[146:149], v[134:137], v[150:153], 0
	v_mfma_f32_16x16x32_bf16 v[150:153], v[126:129], v[158:161], 0
	v_mfma_f32_16x16x32_bf16 v[126:129], v[126:129], v[166:169], 0
	v_mfma_f32_16x16x32_bf16 v[90:93], v[130:133], v[154:157], v[90:93]
	v_mfma_f32_16x16x32_bf16 v[146:149], v[138:141], v[154:157], v[146:149]
	v_mfma_f32_16x16x32_bf16 v[150:153], v[130:133], v[162:165], v[150:153]
	v_mfma_f32_16x16x32_bf16 v[154:157], v[134:137], v[158:161], 0
	v_mfma_f32_16x16x32_bf16 v[126:129], v[130:133], v[170:173], v[126:129]
	v_mfma_f32_16x16x32_bf16 v[130:133], v[134:137], v[166:169], 0
	v_mfma_f32_16x16x32_bf16 v[154:157], v[138:141], v[162:165], v[154:157]
	v_mfma_f32_16x16x32_bf16 v[130:133], v[138:141], v[170:173], v[130:133]
	s_barrier
	ds_read_b128 v[134:137], v43
	ds_read_b128 v[138:141], v43 offset:1024
	ds_read_b128 v[158:161], v43 offset:2048
	ds_read_b128 v[162:165], v43 offset:3072
	s_mov_b32 m0, s37
	ds_read_b128 v[166:169], v41 offset:32768
	ds_read_b128 v[170:173], v41 offset:33792
	ds_read_b128 v[198:201], v41 offset:34816
	ds_read_b128 v[202:205], v41 offset:35840
	ds_read_b128 v[206:209], v41 offset:36864
	ds_read_b128 v[210:213], v41 offset:37888
	ds_read_b128 v[214:217], v41 offset:38912
	ds_read_b128 v[218:221], v41 offset:39936
	global_load_lds_dwordx4 v[26:27], off
	s_mov_b32 m0, s38
	s_nop 0
	global_load_lds_dwordx4 v[28:29], off
	s_waitcnt lgkmcnt(8)
	s_barrier
	s_waitcnt lgkmcnt(0)
	s_waitcnt lgkmcnt(0)
	v_mfma_f32_16x16x32_bf16 v[94:97], v[134:137], v[166:169], v[94:97]
	v_mfma_f32_16x16x32_bf16 v[98:101], v[158:161], v[166:169], v[98:101]
	v_mfma_f32_16x16x32_bf16 v[102:105], v[134:137], v[198:201], v[102:105]
	v_mfma_f32_16x16x32_bf16 v[106:109], v[158:161], v[198:201], v[106:109]
	v_mfma_f32_16x16x32_bf16 v[110:113], v[134:137], v[206:209], v[110:113]
	v_mfma_f32_16x16x32_bf16 v[114:117], v[158:161], v[206:209], v[114:117]
	v_mfma_f32_16x16x32_bf16 v[118:121], v[134:137], v[214:217], v[118:121]
	v_mfma_f32_16x16x32_bf16 v[122:125], v[158:161], v[214:217], v[122:125]
	v_mfma_f32_16x16x32_bf16 v[94:97], v[138:141], v[170:173], v[94:97]
	v_mfma_f32_16x16x32_bf16 v[98:101], v[162:165], v[170:173], v[98:101]
	v_mfma_f32_16x16x32_bf16 v[102:105], v[138:141], v[202:205], v[102:105]
	v_mfma_f32_16x16x32_bf16 v[106:109], v[162:165], v[202:205], v[106:109]
	v_mfma_f32_16x16x32_bf16 v[110:113], v[138:141], v[210:213], v[110:113]
	v_mfma_f32_16x16x32_bf16 v[114:117], v[162:165], v[210:213], v[114:117]
	v_mfma_f32_16x16x32_bf16 v[118:121], v[138:141], v[218:221], v[118:121]
	v_mfma_f32_16x16x32_bf16 v[122:125], v[162:165], v[218:221], v[122:125]
	s_barrier
	s_mov_b32 m0, s51
	v_lshl_add_u64 v[238:239], v[238:239], 0, s[8:9]
	ds_read_b128 v[222:225], v44
	ds_read_b128 v[226:229], v44 offset:1024
	ds_read_b128 v[230:233], v44 offset:2048
	ds_read_b128 v[234:237], v44 offset:3072
	global_load_lds_dwordx4 v[238:239], off
	v_lshl_add_u64 v[238:239], v[240:241], 0, s[8:9]
	s_mov_b32 m0, s52
	s_nop 0
	global_load_lds_dwordx4 v[238:239], off
	s_barrier
	s_waitcnt lgkmcnt(0)
	s_waitcnt lgkmcnt(0)
	v_mfma_f32_16x16x32_bf16 v[142:145], v[222:225], v[166:169], v[142:145]
	v_mfma_f32_16x16x32_bf16 v[62:65], v[230:233], v[166:169], v[62:65]
	v_mfma_f32_16x16x32_bf16 v[66:69], v[222:225], v[198:201], v[66:69]
	v_mfma_f32_16x16x32_bf16 v[70:73], v[230:233], v[198:201], v[70:73]
	v_mfma_f32_16x16x32_bf16 v[74:77], v[222:225], v[206:209], v[74:77]
	v_mfma_f32_16x16x32_bf16 v[78:81], v[230:233], v[206:209], v[78:81]
	v_mfma_f32_16x16x32_bf16 v[82:85], v[222:225], v[214:217], v[82:85]
	v_mfma_f32_16x16x32_bf16 v[86:89], v[230:233], v[214:217], v[86:89]
	v_mfma_f32_16x16x32_bf16 v[142:145], v[226:229], v[170:173], v[142:145]
	v_mfma_f32_16x16x32_bf16 v[62:65], v[234:237], v[170:173], v[62:65]
	v_mfma_f32_16x16x32_bf16 v[66:69], v[226:229], v[202:205], v[66:69]
	v_mfma_f32_16x16x32_bf16 v[70:73], v[234:237], v[202:205], v[70:73]
	v_mfma_f32_16x16x32_bf16 v[74:77], v[226:229], v[210:213], v[74:77]
	v_mfma_f32_16x16x32_bf16 v[78:81], v[234:237], v[210:213], v[78:81]
	v_mfma_f32_16x16x32_bf16 v[82:85], v[226:229], v[218:221], v[82:85]
	v_mfma_f32_16x16x32_bf16 v[86:89], v[234:237], v[218:221], v[86:89]
	s_mov_b32 m0, s40
	s_barrier
	ds_read_b128 v[166:169], v41 offset:49152
	ds_read_b128 v[170:173], v41 offset:50176
	ds_read_b128 v[198:201], v41 offset:51200
	ds_read_b128 v[202:205], v41 offset:52224
	ds_read_b128 v[206:209], v41 offset:53248
	ds_read_b128 v[210:213], v41 offset:54272
	ds_read_b128 v[214:217], v41 offset:55296
	ds_read_b128 v[218:221], v41 offset:56320
	global_load_lds_dwordx4 v[30:31], off
	s_mov_b32 m0, s41
	s_nop 0
	global_load_lds_dwordx4 v[32:33], off
	s_barrier
	s_waitcnt lgkmcnt(0)
	s_waitcnt lgkmcnt(0)
	v_mfma_f32_16x16x32_bf16 v[174:177], v[134:137], v[166:169], v[174:177]
	v_mfma_f32_16x16x32_bf16 v[178:181], v[158:161], v[166:169], v[178:181]
	v_mfma_f32_16x16x32_bf16 v[182:185], v[134:137], v[198:201], v[182:185]
	v_mfma_f32_16x16x32_bf16 v[186:189], v[158:161], v[198:201], v[186:189]
	v_mfma_f32_16x16x32_bf16 v[190:193], v[134:137], v[206:209], v[190:193]
	v_mfma_f32_16x16x32_bf16 v[194:197], v[158:161], v[206:209], v[194:197]
	v_mfma_f32_16x16x32_bf16 v[46:49], v[134:137], v[214:217], v[46:49]
	v_mfma_f32_16x16x32_bf16 v[50:53], v[158:161], v[214:217], v[50:53]
	v_mfma_f32_16x16x32_bf16 v[174:177], v[138:141], v[170:173], v[174:177]
	v_mfma_f32_16x16x32_bf16 v[178:181], v[162:165], v[170:173], v[178:181]
	v_mfma_f32_16x16x32_bf16 v[182:185], v[138:141], v[202:205], v[182:185]
	v_mfma_f32_16x16x32_bf16 v[186:189], v[162:165], v[202:205], v[186:189]
	v_mfma_f32_16x16x32_bf16 v[190:193], v[138:141], v[210:213], v[190:193]
	v_mfma_f32_16x16x32_bf16 v[194:197], v[162:165], v[210:213], v[194:197]
	v_mfma_f32_16x16x32_bf16 v[46:49], v[138:141], v[218:221], v[46:49]
	v_mfma_f32_16x16x32_bf16 v[50:53], v[162:165], v[218:221], v[50:53]
	s_barrier
	s_add_u32 s34, s34, 0x10180
	s_addc_u32 s35, s35, 0
	s_mov_b32 m0, s53
	v_lshl_add_u64 v[134:135], s[34:35], 0, v[2:3]
	global_load_lds_dwordx4 v[134:135], off
	v_lshl_add_u64 v[134:135], s[34:35], 0, v[4:5]
	s_mov_b32 m0, s54
	s_nop 0
	global_load_lds_dwordx4 v[134:135], off
	s_waitcnt vmcnt(6)
	s_barrier
	v_mfma_f32_16x16x32_bf16 v[54:57], v[222:225], v[166:169], v[54:57]
	v_mfma_f32_16x16x32_bf16 v[58:61], v[230:233], v[166:169], v[58:61]
	v_mfma_f32_16x16x32_bf16 v[90:93], v[222:225], v[198:201], v[90:93]
	v_mfma_f32_16x16x32_bf16 v[134:137], v[230:233], v[198:201], v[146:149]
	v_mfma_f32_16x16x32_bf16 v[138:141], v[222:225], v[206:209], v[150:153]
	v_mfma_f32_16x16x32_bf16 v[146:149], v[230:233], v[206:209], v[154:157]
	v_mfma_f32_16x16x32_bf16 v[126:129], v[222:225], v[214:217], v[126:129]
	v_mfma_f32_16x16x32_bf16 v[130:133], v[230:233], v[214:217], v[130:133]
	v_mfma_f32_16x16x32_bf16 v[54:57], v[226:229], v[170:173], v[54:57]
	v_mfma_f32_16x16x32_bf16 v[58:61], v[234:237], v[170:173], v[58:61]
	v_mfma_f32_16x16x32_bf16 v[90:93], v[226:229], v[202:205], v[90:93]
	v_mfma_f32_16x16x32_bf16 v[134:137], v[234:237], v[202:205], v[134:137]
	v_mfma_f32_16x16x32_bf16 v[138:141], v[226:229], v[210:213], v[138:141]
	v_mfma_f32_16x16x32_bf16 v[146:149], v[234:237], v[210:213], v[146:149]
	v_mfma_f32_16x16x32_bf16 v[126:129], v[226:229], v[218:221], v[126:129]
	v_mfma_f32_16x16x32_bf16 v[130:133], v[234:237], v[218:221], v[130:133]
	s_barrier
	ds_read_b128 v[150:153], v40
	ds_read_b128 v[154:157], v40 offset:1024
	ds_read_b128 v[158:161], v40 offset:2048
	ds_read_b128 v[162:165], v40 offset:3072
	s_mov_b32 m0, s45
	ds_read_b128 v[166:169], v41
	ds_read_b128 v[170:173], v41 offset:1024
	ds_read_b128 v[198:201], v41 offset:2048
	ds_read_b128 v[202:205], v41 offset:3072
	ds_read_b128 v[206:209], v41 offset:4096
	ds_read_b128 v[210:213], v41 offset:5120
	ds_read_b128 v[214:217], v41 offset:6144
	ds_read_b128 v[218:221], v41 offset:7168
	global_load_lds_dwordx4 v[34:35], off
	s_mov_b32 m0, s46
	s_nop 0
	global_load_lds_dwordx4 v[36:37], off
	s_waitcnt lgkmcnt(8)
	s_barrier
	s_waitcnt lgkmcnt(0)
	s_waitcnt lgkmcnt(0)
	v_mfma_f32_16x16x32_bf16 v[94:97], v[150:153], v[166:169], v[94:97]
	v_mfma_f32_16x16x32_bf16 v[98:101], v[158:161], v[166:169], v[98:101]
	v_mfma_f32_16x16x32_bf16 v[102:105], v[150:153], v[198:201], v[102:105]
	v_mfma_f32_16x16x32_bf16 v[106:109], v[158:161], v[198:201], v[106:109]
	v_mfma_f32_16x16x32_bf16 v[110:113], v[150:153], v[206:209], v[110:113]
	v_mfma_f32_16x16x32_bf16 v[114:117], v[158:161], v[206:209], v[114:117]
	v_mfma_f32_16x16x32_bf16 v[118:121], v[150:153], v[214:217], v[118:121]
	v_mfma_f32_16x16x32_bf16 v[122:125], v[158:161], v[214:217], v[122:125]
	v_mfma_f32_16x16x32_bf16 v[94:97], v[154:157], v[170:173], v[94:97]
	v_mfma_f32_16x16x32_bf16 v[98:101], v[162:165], v[170:173], v[98:101]
	v_mfma_f32_16x16x32_bf16 v[102:105], v[154:157], v[202:205], v[102:105]
	v_mfma_f32_16x16x32_bf16 v[106:109], v[162:165], v[202:205], v[106:109]
	v_mfma_f32_16x16x32_bf16 v[110:113], v[154:157], v[210:213], v[110:113]
	v_mfma_f32_16x16x32_bf16 v[114:117], v[162:165], v[210:213], v[114:117]
	v_mfma_f32_16x16x32_bf16 v[118:121], v[154:157], v[218:221], v[118:121]
	v_mfma_f32_16x16x32_bf16 v[122:125], v[162:165], v[218:221], v[122:125]
	s_barrier
	s_mov_b32 m0, s47
	v_lshl_add_u64 v[238:239], s[30:31], 0, v[2:3]
	ds_read_b128 v[222:225], v42
	ds_read_b128 v[226:229], v42 offset:1024
	ds_read_b128 v[230:233], v42 offset:2048
	ds_read_b128 v[234:237], v42 offset:3072
	global_load_lds_dwordx4 v[238:239], off
	v_lshl_add_u64 v[240:241], s[30:31], 0, v[4:5]
	s_mov_b32 m0, s48
	s_nop 0
	global_load_lds_dwordx4 v[240:241], off
	s_barrier
	s_waitcnt lgkmcnt(0)
	s_waitcnt lgkmcnt(0)
	v_mfma_f32_16x16x32_bf16 v[142:145], v[222:225], v[166:169], v[142:145]
	v_mfma_f32_16x16x32_bf16 v[62:65], v[230:233], v[166:169], v[62:65]
	v_mfma_f32_16x16x32_bf16 v[66:69], v[222:225], v[198:201], v[66:69]
	v_mfma_f32_16x16x32_bf16 v[70:73], v[230:233], v[198:201], v[70:73]
	v_mfma_f32_16x16x32_bf16 v[74:77], v[222:225], v[206:209], v[74:77]
	v_mfma_f32_16x16x32_bf16 v[78:81], v[230:233], v[206:209], v[78:81]
	v_mfma_f32_16x16x32_bf16 v[82:85], v[222:225], v[214:217], v[82:85]
	v_mfma_f32_16x16x32_bf16 v[86:89], v[230:233], v[214:217], v[86:89]
	v_mfma_f32_16x16x32_bf16 v[142:145], v[226:229], v[170:173], v[142:145]
	v_mfma_f32_16x16x32_bf16 v[62:65], v[234:237], v[170:173], v[62:65]
	v_mfma_f32_16x16x32_bf16 v[66:69], v[226:229], v[202:205], v[66:69]
	v_mfma_f32_16x16x32_bf16 v[70:73], v[234:237], v[202:205], v[70:73]
	v_mfma_f32_16x16x32_bf16 v[74:77], v[226:229], v[210:213], v[74:77]
	v_mfma_f32_16x16x32_bf16 v[78:81], v[234:237], v[210:213], v[78:81]
	v_mfma_f32_16x16x32_bf16 v[82:85], v[226:229], v[218:221], v[82:85]
	v_mfma_f32_16x16x32_bf16 v[86:89], v[234:237], v[218:221], v[86:89]
	s_mov_b32 m0, s33
	s_barrier
	ds_read_b128 v[166:169], v41 offset:16384
	ds_read_b128 v[170:173], v41 offset:17408
	ds_read_b128 v[198:201], v41 offset:18432
	ds_read_b128 v[202:205], v41 offset:19456
	ds_read_b128 v[206:209], v41 offset:20480
	ds_read_b128 v[210:213], v41 offset:21504
	ds_read_b128 v[214:217], v41 offset:22528
	ds_read_b128 v[218:221], v41 offset:23552
	global_load_lds_dwordx4 v[6:7], off
	s_mov_b32 m0, s36
	s_nop 0
	global_load_lds_dwordx4 v[8:9], off
	s_barrier
	s_waitcnt lgkmcnt(0)
	s_waitcnt lgkmcnt(0)
	v_mfma_f32_16x16x32_bf16 v[174:177], v[150:153], v[166:169], v[174:177]
	v_mfma_f32_16x16x32_bf16 v[178:181], v[158:161], v[166:169], v[178:181]
	v_mfma_f32_16x16x32_bf16 v[182:185], v[150:153], v[198:201], v[182:185]
	v_mfma_f32_16x16x32_bf16 v[186:189], v[158:161], v[198:201], v[186:189]
	v_mfma_f32_16x16x32_bf16 v[190:193], v[150:153], v[206:209], v[190:193]
	v_mfma_f32_16x16x32_bf16 v[194:197], v[158:161], v[206:209], v[194:197]
	v_mfma_f32_16x16x32_bf16 v[46:49], v[150:153], v[214:217], v[46:49]
	v_mfma_f32_16x16x32_bf16 v[50:53], v[158:161], v[214:217], v[50:53]
	v_mfma_f32_16x16x32_bf16 v[174:177], v[154:157], v[170:173], v[174:177]
	v_mfma_f32_16x16x32_bf16 v[178:181], v[162:165], v[170:173], v[178:181]
	v_mfma_f32_16x16x32_bf16 v[182:185], v[154:157], v[202:205], v[182:185]
	v_mfma_f32_16x16x32_bf16 v[186:189], v[162:165], v[202:205], v[186:189]
	v_mfma_f32_16x16x32_bf16 v[190:193], v[154:157], v[210:213], v[190:193]
	v_mfma_f32_16x16x32_bf16 v[194:197], v[162:165], v[210:213], v[194:197]
	v_mfma_f32_16x16x32_bf16 v[46:49], v[154:157], v[218:221], v[46:49]
	v_mfma_f32_16x16x32_bf16 v[50:53], v[162:165], v[218:221], v[50:53]
	s_barrier
	s_add_u32 s34, s30, 0x10000
	s_addc_u32 s35, s31, 0
	s_mov_b32 m0, s49
	v_lshl_add_u64 v[150:151], s[34:35], 0, v[2:3]
	global_load_lds_dwordx4 v[150:151], off
	v_lshl_add_u64 v[150:151], s[34:35], 0, v[4:5]
	s_mov_b32 m0, s50
	s_nop 0
	global_load_lds_dwordx4 v[150:151], off
	s_waitcnt vmcnt(6)
	s_barrier
	v_mfma_f32_16x16x32_bf16 v[54:57], v[222:225], v[166:169], v[54:57]
	v_mfma_f32_16x16x32_bf16 v[58:61], v[230:233], v[166:169], v[58:61]
	v_mfma_f32_16x16x32_bf16 v[90:93], v[222:225], v[198:201], v[90:93]
	v_mfma_f32_16x16x32_bf16 v[134:137], v[230:233], v[198:201], v[134:137]
	v_mfma_f32_16x16x32_bf16 v[138:141], v[222:225], v[206:209], v[138:141]
	v_mfma_f32_16x16x32_bf16 v[146:149], v[230:233], v[206:209], v[146:149]
	v_mfma_f32_16x16x32_bf16 v[126:129], v[222:225], v[214:217], v[126:129]
	v_mfma_f32_16x16x32_bf16 v[130:133], v[230:233], v[214:217], v[130:133]
	v_mfma_f32_16x16x32_bf16 v[54:57], v[226:229], v[170:173], v[54:57]
	v_mfma_f32_16x16x32_bf16 v[58:61], v[234:237], v[170:173], v[58:61]
	v_mfma_f32_16x16x32_bf16 v[90:93], v[226:229], v[202:205], v[90:93]
	v_mfma_f32_16x16x32_bf16 v[134:137], v[234:237], v[202:205], v[134:137]
	v_mfma_f32_16x16x32_bf16 v[138:141], v[226:229], v[210:213], v[138:141]
	v_mfma_f32_16x16x32_bf16 v[146:149], v[234:237], v[210:213], v[146:149]
	v_mfma_f32_16x16x32_bf16 v[126:129], v[226:229], v[218:221], v[126:129]
	v_mfma_f32_16x16x32_bf16 v[130:133], v[234:237], v[218:221], v[130:133]
	s_barrier
	ds_read_b128 v[150:153], v43
	ds_read_b128 v[154:157], v43 offset:1024
	ds_read_b128 v[158:161], v43 offset:2048
	ds_read_b128 v[162:165], v43 offset:3072
	s_mov_b32 m0, s37
	ds_read_b128 v[166:169], v41 offset:32768
	ds_read_b128 v[170:173], v41 offset:33792
	ds_read_b128 v[198:201], v41 offset:34816
	ds_read_b128 v[202:205], v41 offset:35840
	ds_read_b128 v[206:209], v41 offset:36864
	ds_read_b128 v[210:213], v41 offset:37888
	ds_read_b128 v[214:217], v41 offset:38912
	ds_read_b128 v[218:221], v41 offset:39936
	global_load_lds_dwordx4 v[10:11], off
	s_mov_b32 m0, s38
	s_nop 0
	global_load_lds_dwordx4 v[16:17], off
	s_waitcnt lgkmcnt(8)
	s_barrier
	s_waitcnt lgkmcnt(0)
	s_waitcnt lgkmcnt(0)
	v_mfma_f32_16x16x32_bf16 v[94:97], v[150:153], v[166:169], v[94:97]
	v_mfma_f32_16x16x32_bf16 v[98:101], v[158:161], v[166:169], v[98:101]
	v_mfma_f32_16x16x32_bf16 v[102:105], v[150:153], v[198:201], v[102:105]
	v_mfma_f32_16x16x32_bf16 v[106:109], v[158:161], v[198:201], v[106:109]
	v_mfma_f32_16x16x32_bf16 v[110:113], v[150:153], v[206:209], v[110:113]
	v_mfma_f32_16x16x32_bf16 v[114:117], v[158:161], v[206:209], v[114:117]
	v_mfma_f32_16x16x32_bf16 v[118:121], v[150:153], v[214:217], v[118:121]
	v_mfma_f32_16x16x32_bf16 v[122:125], v[158:161], v[214:217], v[122:125]
	v_mfma_f32_16x16x32_bf16 v[94:97], v[154:157], v[170:173], v[94:97]
	v_mfma_f32_16x16x32_bf16 v[98:101], v[162:165], v[170:173], v[98:101]
	v_mfma_f32_16x16x32_bf16 v[102:105], v[154:157], v[202:205], v[102:105]
	v_mfma_f32_16x16x32_bf16 v[106:109], v[162:165], v[202:205], v[106:109]
	v_mfma_f32_16x16x32_bf16 v[110:113], v[154:157], v[210:213], v[110:113]
	v_mfma_f32_16x16x32_bf16 v[114:117], v[162:165], v[210:213], v[114:117]
	v_mfma_f32_16x16x32_bf16 v[118:121], v[154:157], v[218:221], v[118:121]
	v_mfma_f32_16x16x32_bf16 v[122:125], v[162:165], v[218:221], v[122:125]
	s_barrier
	s_mov_b32 m0, s51
	v_lshl_add_u64 v[238:239], v[238:239], 0, s[0:1]
	ds_read_b128 v[222:225], v44
	ds_read_b128 v[226:229], v44 offset:1024
	ds_read_b128 v[230:233], v44 offset:2048
	ds_read_b128 v[234:237], v44 offset:3072
	global_load_lds_dwordx4 v[238:239], off
	v_lshl_add_u64 v[238:239], v[240:241], 0, s[0:1]
	s_mov_b32 m0, s52
	s_nop 0
	global_load_lds_dwordx4 v[238:239], off
	s_barrier
	s_waitcnt lgkmcnt(0)
	s_waitcnt lgkmcnt(0)
	v_mfma_f32_16x16x32_bf16 v[142:145], v[222:225], v[166:169], v[142:145]
	v_mfma_f32_16x16x32_bf16 v[62:65], v[230:233], v[166:169], v[62:65]
	v_mfma_f32_16x16x32_bf16 v[66:69], v[222:225], v[198:201], v[66:69]
	v_mfma_f32_16x16x32_bf16 v[70:73], v[230:233], v[198:201], v[70:73]
	v_mfma_f32_16x16x32_bf16 v[74:77], v[222:225], v[206:209], v[74:77]
	v_mfma_f32_16x16x32_bf16 v[78:81], v[230:233], v[206:209], v[78:81]
	v_mfma_f32_16x16x32_bf16 v[82:85], v[222:225], v[214:217], v[82:85]
	v_mfma_f32_16x16x32_bf16 v[86:89], v[230:233], v[214:217], v[86:89]
	v_mfma_f32_16x16x32_bf16 v[142:145], v[226:229], v[170:173], v[142:145]
	v_mfma_f32_16x16x32_bf16 v[62:65], v[234:237], v[170:173], v[62:65]
	v_mfma_f32_16x16x32_bf16 v[66:69], v[226:229], v[202:205], v[66:69]
	v_mfma_f32_16x16x32_bf16 v[70:73], v[234:237], v[202:205], v[70:73]
	v_mfma_f32_16x16x32_bf16 v[74:77], v[226:229], v[210:213], v[74:77]
	v_mfma_f32_16x16x32_bf16 v[78:81], v[234:237], v[210:213], v[78:81]
	v_mfma_f32_16x16x32_bf16 v[82:85], v[226:229], v[218:221], v[82:85]
	v_mfma_f32_16x16x32_bf16 v[86:89], v[234:237], v[218:221], v[86:89]
	s_mov_b32 m0, s40
	s_barrier
	ds_read_b128 v[166:169], v41 offset:49152
	ds_read_b128 v[170:173], v41 offset:50176
	ds_read_b128 v[198:201], v41 offset:51200
	ds_read_b128 v[202:205], v41 offset:52224
	ds_read_b128 v[206:209], v41 offset:53248
	ds_read_b128 v[210:213], v41 offset:54272
	ds_read_b128 v[214:217], v41 offset:55296
	ds_read_b128 v[218:221], v41 offset:56320
	global_load_lds_dwordx4 v[12:13], off
	s_mov_b32 m0, s41
	s_nop 0
	global_load_lds_dwordx4 v[14:15], off
	s_barrier
	s_waitcnt lgkmcnt(0)
	s_waitcnt lgkmcnt(0)
	v_mfma_f32_16x16x32_bf16 v[174:177], v[150:153], v[166:169], v[174:177]
	v_mfma_f32_16x16x32_bf16 v[178:181], v[158:161], v[166:169], v[178:181]
	v_mfma_f32_16x16x32_bf16 v[182:185], v[150:153], v[198:201], v[182:185]
	v_mfma_f32_16x16x32_bf16 v[186:189], v[158:161], v[198:201], v[186:189]
	v_mfma_f32_16x16x32_bf16 v[190:193], v[150:153], v[206:209], v[190:193]
	v_mfma_f32_16x16x32_bf16 v[194:197], v[158:161], v[206:209], v[194:197]
	v_mfma_f32_16x16x32_bf16 v[46:49], v[150:153], v[214:217], v[46:49]
	v_mfma_f32_16x16x32_bf16 v[50:53], v[158:161], v[214:217], v[50:53]
	v_mfma_f32_16x16x32_bf16 v[174:177], v[154:157], v[170:173], v[174:177]
	v_mfma_f32_16x16x32_bf16 v[178:181], v[162:165], v[170:173], v[178:181]
	v_mfma_f32_16x16x32_bf16 v[182:185], v[154:157], v[202:205], v[182:185]
	v_mfma_f32_16x16x32_bf16 v[186:189], v[162:165], v[202:205], v[186:189]
	v_mfma_f32_16x16x32_bf16 v[190:193], v[154:157], v[210:213], v[190:193]
	v_mfma_f32_16x16x32_bf16 v[194:197], v[162:165], v[210:213], v[194:197]
	v_mfma_f32_16x16x32_bf16 v[46:49], v[154:157], v[218:221], v[46:49]
	v_mfma_f32_16x16x32_bf16 v[50:53], v[162:165], v[218:221], v[50:53]
	s_barrier
	s_add_u32 s30, s30, 0x10080
	s_addc_u32 s31, s31, 0
	s_mov_b32 m0, s53
	v_lshl_add_u64 v[150:151], s[30:31], 0, v[2:3]
	global_load_lds_dwordx4 v[150:151], off
	v_lshl_add_u64 v[150:151], s[30:31], 0, v[4:5]
	s_mov_b32 m0, s54
	s_nop 0
	global_load_lds_dwordx4 v[150:151], off
	s_waitcnt vmcnt(6)
	s_barrier
	v_mfma_f32_16x16x32_bf16 v[54:57], v[222:225], v[166:169], v[54:57]
	v_mfma_f32_16x16x32_bf16 v[58:61], v[230:233], v[166:169], v[58:61]
	v_mfma_f32_16x16x32_bf16 v[90:93], v[222:225], v[198:201], v[90:93]
	v_mfma_f32_16x16x32_bf16 v[134:137], v[230:233], v[198:201], v[134:137]
	v_mfma_f32_16x16x32_bf16 v[138:141], v[222:225], v[206:209], v[138:141]
	v_mfma_f32_16x16x32_bf16 v[146:149], v[230:233], v[206:209], v[146:149]
	v_mfma_f32_16x16x32_bf16 v[126:129], v[222:225], v[214:217], v[126:129]
	v_mfma_f32_16x16x32_bf16 v[130:133], v[230:233], v[214:217], v[130:133]
	v_mfma_f32_16x16x32_bf16 v[54:57], v[226:229], v[170:173], v[54:57]
	v_mfma_f32_16x16x32_bf16 v[58:61], v[234:237], v[170:173], v[58:61]
	v_mfma_f32_16x16x32_bf16 v[90:93], v[226:229], v[202:205], v[90:93]
	v_mfma_f32_16x16x32_bf16 v[134:137], v[234:237], v[202:205], v[134:137]
	v_mfma_f32_16x16x32_bf16 v[138:141], v[226:229], v[210:213], v[138:141]
	v_mfma_f32_16x16x32_bf16 v[146:149], v[234:237], v[210:213], v[146:149]
	v_mfma_f32_16x16x32_bf16 v[126:129], v[226:229], v[218:221], v[126:129]
	v_mfma_f32_16x16x32_bf16 v[130:133], v[234:237], v[218:221], v[130:133]
	v_mov_b32_e32 v45, v1
	v_mov_b32_e32 v150, v39
	s_barrier
	v_cvt_pk_bf16_f32 v66, v66, v67
	v_cvt_pk_bf16_f32 v67, v68, v69
	v_cvt_pk_bf16_f32 v68, v70, v71
	v_cvt_pk_bf16_f32 v70, v110, v111
	v_cvt_pk_bf16_f32 v71, v112, v113
	v_add_u32_e32 v110, s44, v45
	v_lshlrev_b32_e32 v112, 3, v150
	v_ashrrev_i32_e32 v111, 31, v110
	v_ashrrev_i32_e32 v113, 31, v112
	v_lshlrev_b64 v[110:111], 11, v[110:111]
	v_lshl_add_u64 v[112:113], s[4:5], 0, v[112:113]
	v_lshl_add_u64 v[110:111], s[24:25], 0, v[110:111]
	v_cvt_pk_bf16_f32 v94, v94, v95
	v_cvt_pk_bf16_f32 v95, v96, v97
	v_cvt_pk_bf16_f32 v96, v98, v99
	v_cvt_pk_bf16_f32 v97, v100, v101
	v_lshl_add_u64 v[110:111], v[112:113], 1, v[110:111]
	v_cvt_pk_bf16_f32 v98, v142, v143
	v_cvt_pk_bf16_f32 v99, v144, v145
	v_cvt_pk_bf16_f32 v100, v62, v63
	v_cvt_pk_bf16_f32 v101, v64, v65
	global_store_dwordx4 v[110:111], v[94:97], off
	global_store_dwordx4 v[110:111], v[98:101], off offset:256
	v_cvt_pk_bf16_f32 v69, v72, v73
	v_add_co_u32_e32 v96, vcc, s43, v110
	v_cvt_pk_bf16_f32 v72, v114, v115
	s_nop 0
	v_addc_co_u32_e32 v97, vcc, 0, v111, vcc
	v_add_co_u32_e32 v100, vcc, s39, v110
	v_cvt_pk_bf16_f32 v74, v74, v75
	s_nop 0
	v_addc_co_u32_e32 v101, vcc, 0, v111, vcc
	v_add_co_u32_e32 v114, vcc, s42, v110
	v_cvt_pk_bf16_f32 v75, v76, v77
	s_nop 0
	v_addc_co_u32_e32 v115, vcc, 0, v111, vcc
	v_cvt_pk_bf16_f32 v76, v78, v79
	v_cvt_pk_bf16_f32 v78, v118, v119
	v_add_co_u32_e32 v118, vcc, s55, v110
	v_cvt_pk_bf16_f32 v77, v80, v81
	s_nop 0
	v_addc_co_u32_e32 v119, vcc, 0, v111, vcc
	v_cvt_pk_bf16_f32 v80, v122, v123
	v_add_co_u32_e32 v122, vcc, s56, v110
	v_cvt_pk_bf16_f32 v46, v46, v47
	s_nop 0
	v_addc_co_u32_e32 v123, vcc, 0, v111, vcc
	v_cvt_pk_bf16_f32 v47, v48, v49
	v_cvt_pk_bf16_f32 v48, v50, v51
	v_cvt_pk_bf16_f32 v50, v126, v127
	s_add_u32 s4, s4, 0x100
	v_add_co_u32_e32 v126, vcc, s57, v110
	s_addc_u32 s5, s5, 0
	s_nop 0
	v_addc_co_u32_e32 v127, vcc, 0, v111, vcc
	v_cvt_pk_bf16_f32 v62, v102, v103
	v_cvt_pk_bf16_f32 v63, v104, v105
	v_cvt_pk_bf16_f32 v64, v106, v107
	v_cvt_pk_bf16_f32 v65, v108, v109
	v_cvt_pk_bf16_f32 v73, v116, v117
	v_cvt_pk_bf16_f32 v79, v120, v121
	v_cvt_pk_bf16_f32 v81, v124, v125
	v_cvt_pk_bf16_f32 v49, v52, v53
	v_cvt_pk_bf16_f32 v51, v128, v129
	v_cvt_pk_bf16_f32 v52, v130, v131
	v_cvt_pk_bf16_f32 v53, v132, v133
	s_mov_b32 s31, s59
	s_mov_b32 s30, s59
	s_mov_b64 s[34:35], s[28:29]
	s_cmp_lg_u32 s59, 4
	v_lshl_add_u64 v[94:95], v[110:111], 0, s[12:13]
	v_lshl_add_u64 v[98:99], v[110:111], 0, s[10:11]
	v_lshl_add_u64 v[112:113], v[110:111], 0, s[14:15]
	v_lshl_add_u64 v[116:117], v[110:111], 0, s[16:17]
	v_lshl_add_u64 v[120:121], v[110:111], 0, s[18:19]
	v_lshl_add_u64 v[124:125], v[110:111], 0, s[20:21]
	v_lshl_add_u64 v[128:129], v[110:111], 0, s[22:23]
	v_add_co_u32_e32 v110, vcc, s58, v110
	v_cvt_pk_bf16_f32 v82, v82, v83
	v_cvt_pk_bf16_f32 v83, v84, v85
	v_cvt_pk_bf16_f32 v84, v86, v87
	v_cvt_pk_bf16_f32 v85, v88, v89
	v_cvt_pk_bf16_f32 v86, v174, v175
	v_cvt_pk_bf16_f32 v87, v176, v177
	v_cvt_pk_bf16_f32 v88, v178, v179
	v_cvt_pk_bf16_f32 v89, v180, v181
	v_cvt_pk_bf16_f32 v54, v54, v55
	v_cvt_pk_bf16_f32 v55, v56, v57
	v_cvt_pk_bf16_f32 v56, v58, v59
	v_cvt_pk_bf16_f32 v57, v60, v61
	v_cvt_pk_bf16_f32 v58, v182, v183
	v_cvt_pk_bf16_f32 v59, v184, v185
	v_cvt_pk_bf16_f32 v60, v186, v187
	v_cvt_pk_bf16_f32 v61, v188, v189
	v_cvt_pk_bf16_f32 v90, v90, v91
	v_cvt_pk_bf16_f32 v91, v92, v93
	v_cvt_pk_bf16_f32 v92, v134, v135
	v_cvt_pk_bf16_f32 v93, v136, v137
	v_cvt_pk_bf16_f32 v102, v190, v191
	v_cvt_pk_bf16_f32 v103, v192, v193
	v_cvt_pk_bf16_f32 v104, v194, v195
	v_cvt_pk_bf16_f32 v105, v196, v197
	v_cvt_pk_bf16_f32 v106, v138, v139
	v_cvt_pk_bf16_f32 v107, v140, v141
	v_cvt_pk_bf16_f32 v108, v146, v147
	v_cvt_pk_bf16_f32 v109, v148, v149
	global_store_dwordx4 v[96:97], v[62:65], off
	global_store_dwordx4 v[94:95], v[66:69], off offset:256
	global_store_dwordx4 v[100:101], v[70:73], off
	global_store_dwordx4 v[98:99], v[74:77], off offset:256
	global_store_dwordx4 v[114:115], v[78:81], off
	global_store_dwordx4 v[112:113], v[82:85], off offset:256
	global_store_dwordx4 v[118:119], v[86:89], off
	global_store_dwordx4 v[116:117], v[54:57], off offset:256
	global_store_dwordx4 v[122:123], v[58:61], off
	global_store_dwordx4 v[120:121], v[90:93], off offset:256
	global_store_dwordx4 v[126:127], v[102:105], off
	global_store_dwordx4 v[124:125], v[106:109], off offset:256
	v_addc_co_u32_e32 v111, vcc, 0, v111, vcc
	global_store_dwordx4 v[128:129], v[50:53], off offset:256
	global_store_dwordx4 v[110:111], v[46:49], off
	s_cbranch_scc1 .LBB0_517
	s_waitcnt vmcnt(0)
	s_cmpk_gt_u32 s3, 0xff
	s_cbranch_scc1 .LBB0_520
	s_barrier

.LBB0_530:
	s_add_u32 s16, s6, s14
	ds_read_b128 v[130:133], v1
	ds_read_b128 v[134:137], v1 offset:1024
	ds_read_b128 v[138:141], v1 offset:2048
	ds_read_b128 v[142:145], v1 offset:3072
	s_addc_u32 s17, s7, s15
	s_add_u32 s16, s16, 0x100
	s_addc_u32 s17, s17, 0
	s_add_u32 s55, s52, s14
	s_addc_u32 s56, s53, s15
	s_cmpk_eq_i32 s14, 0x700
	s_cselect_b32 s19, s7, s17
	s_cselect_b32 s18, s6, s16
	s_cselect_b32 s17, s50, s56
	s_cselect_b32 s16, s51, s55
	s_mov_b32 m0, s34
	v_lshl_add_u64 v[196:197], v[192:193], 0, s[14:15]
	ds_read_b128 v[146:149], v210
	ds_read_b128 v[150:153], v210 offset:1024
	ds_read_b128 v[154:157], v210 offset:2048
	ds_read_b128 v[158:161], v210 offset:3072
	ds_read_b128 v[162:165], v210 offset:4096
	ds_read_b128 v[166:169], v210 offset:5120
	ds_read_b128 v[170:173], v210 offset:6144
	ds_read_b128 v[174:177], v210 offset:7168
	global_load_lds_dwordx4 v[196:197], off
	v_lshl_add_u64 v[196:197], v[194:195], 0, s[14:15]
	s_mov_b32 m0, s35
	s_nop 0
	global_load_lds_dwordx4 v[196:197], off
	s_waitcnt lgkmcnt(8)
	s_barrier
	s_waitcnt lgkmcnt(0)
	s_waitcnt lgkmcnt(0)
	v_mfma_f32_16x16x32_bf16 v[126:129], v[130:133], v[146:149], v[126:129]
	v_mfma_f32_16x16x32_bf16 v[122:125], v[138:141], v[146:149], v[122:125]
	v_mfma_f32_16x16x32_bf16 v[110:113], v[130:133], v[154:157], v[110:113]
	v_mfma_f32_16x16x32_bf16 v[106:109], v[138:141], v[154:157], v[106:109]
	v_mfma_f32_16x16x32_bf16 v[94:97], v[130:133], v[162:165], v[94:97]
	v_mfma_f32_16x16x32_bf16 v[90:93], v[138:141], v[162:165], v[90:93]
	v_mfma_f32_16x16x32_bf16 v[78:81], v[130:133], v[170:173], v[78:81]
	v_mfma_f32_16x16x32_bf16 v[74:77], v[138:141], v[170:173], v[74:77]
	v_mfma_f32_16x16x32_bf16 v[126:129], v[134:137], v[150:153], v[126:129]
	v_mfma_f32_16x16x32_bf16 v[122:125], v[142:145], v[150:153], v[122:125]
	v_mfma_f32_16x16x32_bf16 v[110:113], v[134:137], v[158:161], v[110:113]
	v_mfma_f32_16x16x32_bf16 v[106:109], v[142:145], v[158:161], v[106:109]
	v_mfma_f32_16x16x32_bf16 v[94:97], v[134:137], v[166:169], v[94:97]
	v_mfma_f32_16x16x32_bf16 v[90:93], v[142:145], v[166:169], v[90:93]
	v_mfma_f32_16x16x32_bf16 v[78:81], v[134:137], v[174:177], v[78:81]
	v_mfma_f32_16x16x32_bf16 v[74:77], v[142:145], v[174:177], v[74:77]
	s_barrier
	s_mov_b32 m0, s36
	v_lshl_add_u64 v[218:219], s[16:17], 0, v[182:183]
	ds_read_b128 v[196:199], v211
	ds_read_b128 v[200:203], v211 offset:1024
	ds_read_b128 v[204:207], v211 offset:2048
	ds_read_b128 v[214:217], v211 offset:3072
	global_load_lds_dwordx4 v[218:219], off
	v_lshl_add_u64 v[220:221], s[16:17], 0, v[178:179]
	s_mov_b32 m0, s37
	s_nop 0
	global_load_lds_dwordx4 v[220:221], off
	s_barrier
	s_waitcnt lgkmcnt(0)
	s_waitcnt lgkmcnt(0)
	v_mfma_f32_16x16x32_bf16 v[118:121], v[196:199], v[146:149], v[118:121]
	v_mfma_f32_16x16x32_bf16 v[114:117], v[204:207], v[146:149], v[114:117]
	v_mfma_f32_16x16x32_bf16 v[102:105], v[196:199], v[154:157], v[102:105]
	v_mfma_f32_16x16x32_bf16 v[98:101], v[204:207], v[154:157], v[98:101]
	v_mfma_f32_16x16x32_bf16 v[86:89], v[196:199], v[162:165], v[86:89]
	v_mfma_f32_16x16x32_bf16 v[82:85], v[204:207], v[162:165], v[82:85]
	v_mfma_f32_16x16x32_bf16 v[70:73], v[196:199], v[170:173], v[70:73]
	v_mfma_f32_16x16x32_bf16 v[66:69], v[204:207], v[170:173], v[66:69]
	v_mfma_f32_16x16x32_bf16 v[118:121], v[200:203], v[150:153], v[118:121]
	v_mfma_f32_16x16x32_bf16 v[114:117], v[214:217], v[150:153], v[114:117]
	v_mfma_f32_16x16x32_bf16 v[102:105], v[200:203], v[158:161], v[102:105]
	v_mfma_f32_16x16x32_bf16 v[98:101], v[214:217], v[158:161], v[98:101]
	v_mfma_f32_16x16x32_bf16 v[86:89], v[200:203], v[166:169], v[86:89]
	v_mfma_f32_16x16x32_bf16 v[82:85], v[214:217], v[166:169], v[82:85]
	v_mfma_f32_16x16x32_bf16 v[70:73], v[200:203], v[174:177], v[70:73]
	v_mfma_f32_16x16x32_bf16 v[66:69], v[214:217], v[174:177], v[66:69]
	s_mov_b32 m0, s3
	v_lshl_add_u64 v[222:223], s[18:19], 0, v[190:191]
	s_barrier
	ds_read_b128 v[146:149], v210 offset:16384
	ds_read_b128 v[150:153], v210 offset:17408
	ds_read_b128 v[154:157], v210 offset:18432
	ds_read_b128 v[158:161], v210 offset:19456
	ds_read_b128 v[162:165], v210 offset:20480
	ds_read_b128 v[166:169], v210 offset:21504
	ds_read_b128 v[170:173], v210 offset:22528
	ds_read_b128 v[174:177], v210 offset:23552
	global_load_lds_dwordx4 v[222:223], off
	v_lshl_add_u64 v[224:225], s[18:19], 0, v[180:181]
	s_mov_b32 m0, s20
	s_nop 0
	global_load_lds_dwordx4 v[224:225], off
	s_barrier
	s_waitcnt lgkmcnt(0)
	s_waitcnt lgkmcnt(0)
	v_mfma_f32_16x16x32_bf16 v[62:65], v[130:133], v[146:149], v[62:65]
	v_mfma_f32_16x16x32_bf16 v[58:61], v[138:141], v[146:149], v[58:61]
	v_mfma_f32_16x16x32_bf16 v[46:49], v[130:133], v[154:157], v[46:49]
	v_mfma_f32_16x16x32_bf16 v[42:45], v[138:141], v[154:157], v[42:45]
	v_mfma_f32_16x16x32_bf16 v[30:33], v[130:133], v[162:165], v[30:33]
	v_mfma_f32_16x16x32_bf16 v[26:29], v[138:141], v[162:165], v[26:29]
	v_mfma_f32_16x16x32_bf16 v[14:17], v[130:133], v[170:173], v[14:17]
	v_mfma_f32_16x16x32_bf16 v[10:13], v[138:141], v[170:173], v[10:13]
	v_mfma_f32_16x16x32_bf16 v[62:65], v[134:137], v[150:153], v[62:65]
	v_mfma_f32_16x16x32_bf16 v[58:61], v[142:145], v[150:153], v[58:61]
	v_mfma_f32_16x16x32_bf16 v[46:49], v[134:137], v[158:161], v[46:49]
	v_mfma_f32_16x16x32_bf16 v[42:45], v[142:145], v[158:161], v[42:45]
	v_mfma_f32_16x16x32_bf16 v[30:33], v[134:137], v[166:169], v[30:33]
	v_mfma_f32_16x16x32_bf16 v[26:29], v[142:145], v[166:169], v[26:29]
	v_mfma_f32_16x16x32_bf16 v[14:17], v[134:137], v[174:177], v[14:17]
	v_mfma_f32_16x16x32_bf16 v[10:13], v[142:145], v[174:177], v[10:13]
	s_barrier
	s_add_u32 s56, s16, 0x40000
	s_addc_u32 s57, s17, 0
	s_mov_b32 m0, s38
	v_lshl_add_u64 v[130:131], s[56:57], 0, v[182:183]
	global_load_lds_dwordx4 v[130:131], off
	v_lshl_add_u64 v[130:131], s[56:57], 0, v[178:179]
	s_mov_b32 m0, s39
	s_nop 0
	global_load_lds_dwordx4 v[130:131], off
	s_waitcnt vmcnt(6)
	s_barrier
	v_mfma_f32_16x16x32_bf16 v[54:57], v[196:199], v[146:149], v[54:57]
	v_mfma_f32_16x16x32_bf16 v[50:53], v[204:207], v[146:149], v[50:53]
	v_mfma_f32_16x16x32_bf16 v[38:41], v[196:199], v[154:157], v[38:41]
	v_mfma_f32_16x16x32_bf16 v[34:37], v[204:207], v[154:157], v[34:37]
	v_mfma_f32_16x16x32_bf16 v[22:25], v[196:199], v[162:165], v[22:25]
	v_mfma_f32_16x16x32_bf16 v[18:21], v[204:207], v[162:165], v[18:21]
	v_mfma_f32_16x16x32_bf16 v[6:9], v[196:199], v[170:173], v[6:9]
	v_mfma_f32_16x16x32_bf16 v[2:5], v[204:207], v[170:173], v[2:5]
	v_mfma_f32_16x16x32_bf16 v[54:57], v[200:203], v[150:153], v[54:57]
	v_mfma_f32_16x16x32_bf16 v[50:53], v[214:217], v[150:153], v[50:53]
	v_mfma_f32_16x16x32_bf16 v[38:41], v[200:203], v[158:161], v[38:41]
	v_mfma_f32_16x16x32_bf16 v[34:37], v[214:217], v[158:161], v[34:37]
	v_mfma_f32_16x16x32_bf16 v[22:25], v[200:203], v[166:169], v[22:25]
	v_mfma_f32_16x16x32_bf16 v[18:21], v[214:217], v[166:169], v[18:21]
	v_mfma_f32_16x16x32_bf16 v[6:9], v[200:203], v[174:177], v[6:9]
	v_mfma_f32_16x16x32_bf16 v[2:5], v[214:217], v[174:177], v[2:5]
	s_barrier
	ds_read_b128 v[130:133], v212
	ds_read_b128 v[134:137], v212 offset:1024
	ds_read_b128 v[138:141], v212 offset:2048
	ds_read_b128 v[142:145], v212 offset:3072
	s_add_u32 s18, s18, 0x40000
	s_addc_u32 s19, s19, 0
	s_mov_b32 m0, s21
	v_lshl_add_u64 v[196:197], s[18:19], 0, v[190:191]
	ds_read_b128 v[146:149], v210 offset:32768
	ds_read_b128 v[150:153], v210 offset:33792
	ds_read_b128 v[154:157], v210 offset:34816
	ds_read_b128 v[158:161], v210 offset:35840
	ds_read_b128 v[162:165], v210 offset:36864
	ds_read_b128 v[166:169], v210 offset:37888
	ds_read_b128 v[170:173], v210 offset:38912
	ds_read_b128 v[174:177], v210 offset:39936
	global_load_lds_dwordx4 v[196:197], off
	v_lshl_add_u64 v[196:197], s[18:19], 0, v[180:181]
	s_mov_b32 m0, s22
	s_nop 0
	global_load_lds_dwordx4 v[196:197], off
	s_waitcnt lgkmcnt(8)
	s_barrier
	s_waitcnt lgkmcnt(0)
	s_waitcnt lgkmcnt(0)
	v_mfma_f32_16x16x32_bf16 v[126:129], v[130:133], v[146:149], v[126:129]
	v_mfma_f32_16x16x32_bf16 v[122:125], v[138:141], v[146:149], v[122:125]
	v_mfma_f32_16x16x32_bf16 v[110:113], v[130:133], v[154:157], v[110:113]
	v_mfma_f32_16x16x32_bf16 v[106:109], v[138:141], v[154:157], v[106:109]
	v_mfma_f32_16x16x32_bf16 v[94:97], v[130:133], v[162:165], v[94:97]
	v_mfma_f32_16x16x32_bf16 v[90:93], v[138:141], v[162:165], v[90:93]
	v_mfma_f32_16x16x32_bf16 v[78:81], v[130:133], v[170:173], v[78:81]
	v_mfma_f32_16x16x32_bf16 v[74:77], v[138:141], v[170:173], v[74:77]
	v_mfma_f32_16x16x32_bf16 v[126:129], v[134:137], v[150:153], v[126:129]
	v_mfma_f32_16x16x32_bf16 v[122:125], v[142:145], v[150:153], v[122:125]
	v_mfma_f32_16x16x32_bf16 v[110:113], v[134:137], v[158:161], v[110:113]
	v_mfma_f32_16x16x32_bf16 v[106:109], v[142:145], v[158:161], v[106:109]
	v_mfma_f32_16x16x32_bf16 v[94:97], v[134:137], v[166:169], v[94:97]
	v_mfma_f32_16x16x32_bf16 v[90:93], v[142:145], v[166:169], v[90:93]
	v_mfma_f32_16x16x32_bf16 v[78:81], v[134:137], v[174:177], v[78:81]
	v_mfma_f32_16x16x32_bf16 v[74:77], v[142:145], v[174:177], v[74:77]
	s_barrier
	s_mov_b32 m0, s40
	v_lshl_add_u64 v[218:219], v[218:219], 0, s[0:1]
	ds_read_b128 v[196:199], v213
	ds_read_b128 v[200:203], v213 offset:1024
	ds_read_b128 v[204:207], v213 offset:2048
	ds_read_b128 v[214:217], v213 offset:3072
	global_load_lds_dwordx4 v[218:219], off
	v_lshl_add_u64 v[218:219], v[220:221], 0, s[0:1]
	s_mov_b32 m0, s41
	s_nop 0
	global_load_lds_dwordx4 v[218:219], off
	s_barrier
	s_waitcnt lgkmcnt(0)
	s_waitcnt lgkmcnt(0)
	v_mfma_f32_16x16x32_bf16 v[118:121], v[196:199], v[146:149], v[118:121]
	v_mfma_f32_16x16x32_bf16 v[114:117], v[204:207], v[146:149], v[114:117]
	v_mfma_f32_16x16x32_bf16 v[102:105], v[196:199], v[154:157], v[102:105]
	v_mfma_f32_16x16x32_bf16 v[98:101], v[204:207], v[154:157], v[98:101]
	v_mfma_f32_16x16x32_bf16 v[86:89], v[196:199], v[162:165], v[86:89]
	v_mfma_f32_16x16x32_bf16 v[82:85], v[204:207], v[162:165], v[82:85]
	v_mfma_f32_16x16x32_bf16 v[70:73], v[196:199], v[170:173], v[70:73]
	v_mfma_f32_16x16x32_bf16 v[66:69], v[204:207], v[170:173], v[66:69]
	v_mfma_f32_16x16x32_bf16 v[118:121], v[200:203], v[150:153], v[118:121]
	v_mfma_f32_16x16x32_bf16 v[114:117], v[214:217], v[150:153], v[114:117]
	v_mfma_f32_16x16x32_bf16 v[102:105], v[200:203], v[158:161], v[102:105]
	v_mfma_f32_16x16x32_bf16 v[98:101], v[214:217], v[158:161], v[98:101]
	v_mfma_f32_16x16x32_bf16 v[86:89], v[200:203], v[166:169], v[86:89]
	v_mfma_f32_16x16x32_bf16 v[82:85], v[214:217], v[166:169], v[82:85]
	v_mfma_f32_16x16x32_bf16 v[70:73], v[200:203], v[174:177], v[70:73]
	v_mfma_f32_16x16x32_bf16 v[66:69], v[214:217], v[174:177], v[66:69]
	s_mov_b32 m0, s30
	v_lshl_add_u64 v[218:219], v[222:223], 0, s[0:1]
	s_barrier
	ds_read_b128 v[146:149], v210 offset:49152
	ds_read_b128 v[150:153], v210 offset:50176
	ds_read_b128 v[154:157], v210 offset:51200
	ds_read_b128 v[158:161], v210 offset:52224
	ds_read_b128 v[162:165], v210 offset:53248
	ds_read_b128 v[166:169], v210 offset:54272
	ds_read_b128 v[170:173], v210 offset:55296
	ds_read_b128 v[174:177], v210 offset:56320
	global_load_lds_dwordx4 v[218:219], off
	v_lshl_add_u64 v[218:219], v[224:225], 0, s[0:1]
	s_mov_b32 m0, s31
	s_nop 0
	global_load_lds_dwordx4 v[218:219], off
	s_barrier
	s_waitcnt lgkmcnt(0)
	s_waitcnt lgkmcnt(0)
	v_mfma_f32_16x16x32_bf16 v[62:65], v[130:133], v[146:149], v[62:65]
	v_mfma_f32_16x16x32_bf16 v[58:61], v[138:141], v[146:149], v[58:61]
	v_mfma_f32_16x16x32_bf16 v[46:49], v[130:133], v[154:157], v[46:49]
	v_mfma_f32_16x16x32_bf16 v[42:45], v[138:141], v[154:157], v[42:45]
	v_mfma_f32_16x16x32_bf16 v[30:33], v[130:133], v[162:165], v[30:33]
	v_mfma_f32_16x16x32_bf16 v[26:29], v[138:141], v[162:165], v[26:29]
	v_mfma_f32_16x16x32_bf16 v[14:17], v[130:133], v[170:173], v[14:17]
	v_mfma_f32_16x16x32_bf16 v[10:13], v[138:141], v[170:173], v[10:13]
	v_mfma_f32_16x16x32_bf16 v[62:65], v[134:137], v[150:153], v[62:65]
	v_mfma_f32_16x16x32_bf16 v[58:61], v[142:145], v[150:153], v[58:61]
	v_mfma_f32_16x16x32_bf16 v[46:49], v[134:137], v[158:161], v[46:49]
	v_mfma_f32_16x16x32_bf16 v[42:45], v[142:145], v[158:161], v[42:45]
	v_mfma_f32_16x16x32_bf16 v[30:33], v[134:137], v[166:169], v[30:33]
	v_mfma_f32_16x16x32_bf16 v[26:29], v[142:145], v[166:169], v[26:29]
	v_mfma_f32_16x16x32_bf16 v[14:17], v[134:137], v[174:177], v[14:17]
	v_mfma_f32_16x16x32_bf16 v[10:13], v[142:145], v[174:177], v[10:13]
	s_barrier
	s_add_u32 s16, s16, 0x40080
	s_addc_u32 s17, s17, 0
	s_mov_b32 m0, s42
	v_lshl_add_u64 v[130:131], s[16:17], 0, v[182:183]
	global_load_lds_dwordx4 v[130:131], off
	v_lshl_add_u64 v[130:131], s[16:17], 0, v[178:179]
	s_mov_b32 m0, s43
	s_nop 0
	global_load_lds_dwordx4 v[130:131], off
	s_waitcnt vmcnt(6)
	s_barrier
	v_mfma_f32_16x16x32_bf16 v[54:57], v[196:199], v[146:149], v[54:57]
	v_mfma_f32_16x16x32_bf16 v[50:53], v[204:207], v[146:149], v[50:53]
	v_mfma_f32_16x16x32_bf16 v[38:41], v[196:199], v[154:157], v[38:41]
	v_mfma_f32_16x16x32_bf16 v[34:37], v[204:207], v[154:157], v[34:37]
	v_mfma_f32_16x16x32_bf16 v[22:25], v[196:199], v[162:165], v[22:25]
	v_mfma_f32_16x16x32_bf16 v[18:21], v[204:207], v[162:165], v[18:21]
	v_mfma_f32_16x16x32_bf16 v[6:9], v[196:199], v[170:173], v[6:9]
	v_mfma_f32_16x16x32_bf16 v[2:5], v[204:207], v[170:173], v[2:5]
	v_mfma_f32_16x16x32_bf16 v[54:57], v[200:203], v[150:153], v[54:57]
	v_mfma_f32_16x16x32_bf16 v[50:53], v[214:217], v[150:153], v[50:53]
	v_mfma_f32_16x16x32_bf16 v[38:41], v[200:203], v[158:161], v[38:41]
	v_mfma_f32_16x16x32_bf16 v[34:37], v[214:217], v[158:161], v[34:37]
	v_mfma_f32_16x16x32_bf16 v[22:25], v[200:203], v[166:169], v[22:25]
	v_mfma_f32_16x16x32_bf16 v[18:21], v[214:217], v[166:169], v[18:21]
	v_mfma_f32_16x16x32_bf16 v[6:9], v[200:203], v[174:177], v[6:9]
	v_mfma_f32_16x16x32_bf16 v[2:5], v[214:217], v[174:177], v[2:5]
	s_add_i32 s54, s54, 2
	s_add_u32 s14, s14, 0x100
	s_addc_u32 s15, s15, 0
	s_cmp_gt_u32 s54, 13
	s_barrier
	s_cbranch_scc0 .LBB0_530
	v_mov_b32_e32 v130, v208
	v_mov_b32_e32 v215, v209
	s_lshl_b32 s14, s49, 8
	s_or_b32 s14, s14, s29
	v_add_u32_e32 v214, s28, v130
	v_add_u32_e32 v200, s44, v214
	v_lshl_add_u32 v196, v215, 3, s14
	v_ashrrev_i32_e32 v197, 31, v196
	v_ashrrev_i32_e32 v201, 31, v200
	v_lshl_add_u64 v[198:199], v[196:197], 2, s[60:61]
	v_lshlrev_b64 v[130:131], 12, v[200:201]
	v_lshl_add_u64 v[130:131], v[198:199], 0, v[130:131]
	global_load_dwordx4 v[216:219], v[130:131], off
	global_load_dwordx4 v[220:223], v[130:131], off offset:16
	global_load_dwordx4 v[224:227], v[130:131], off offset:512
	global_load_dwordx4 v[228:231], v[130:131], off offset:528
	v_add_u32_e32 v206, 16, v200
	v_add_u32_e32 v204, 32, v200
	v_add_u32_e32 v202, 48, v200
	v_ashrrev_i32_e32 v207, 31, v206
	v_ashrrev_i32_e32 v205, 31, v204
	v_ashrrev_i32_e32 v203, 31, v202
	v_lshlrev_b64 v[130:131], 12, v[206:207]
	v_lshlrev_b64 v[132:133], 12, v[204:205]
	v_lshlrev_b64 v[134:135], 12, v[202:203]
	v_lshl_add_u64 v[130:131], v[198:199], 0, v[130:131]
	v_lshl_add_u64 v[132:133], v[198:199], 0, v[132:133]
	v_lshl_add_u64 v[134:135], v[198:199], 0, v[134:135]
	global_load_dwordx4 v[170:173], v[130:131], off offset:16
	global_load_dwordx4 v[174:177], v[130:131], off
	global_load_dwordx4 v[162:165], v[130:131], off offset:528
	global_load_dwordx4 v[166:169], v[130:131], off offset:512
	global_load_dwordx4 v[154:157], v[132:133], off offset:16
	global_load_dwordx4 v[158:161], v[132:133], off
	global_load_dwordx4 v[146:149], v[132:133], off offset:528
	global_load_dwordx4 v[150:153], v[132:133], off offset:512
	global_load_dwordx4 v[138:141], v[134:135], off offset:16
	global_load_dwordx4 v[142:145], v[134:135], off
	s_nop 0
	global_load_dwordx4 v[130:133], v[134:135], off offset:528
	s_nop 0
	global_load_dwordx4 v[134:137], v[134:135], off offset:512
	v_lshlrev_b64 v[232:233], 11, v[200:201]
	v_cmp_eq_u32_e32 vcc, 0, v215
	s_waitcnt vmcnt(0)
	v_pk_add_f32 v[126:127], v[126:127], v[216:217]
	v_pk_add_f32 v[128:129], v[128:129], v[218:219]
	v_pk_add_f32 v[118:119], v[118:119], v[224:225]
	v_pk_add_f32 v[218:219], v[114:115], v[228:229]
	v_cvt_pk_bf16_f32 v114, v126, v127
	v_mul_f32_e32 v127, v127, v127
	v_mul_f32_e32 v201, v119, v119
	v_pk_add_f32 v[120:121], v[120:121], v[226:227]
	v_fmac_f32_e32 v127, v126, v126
	v_fmac_f32_e32 v201, v118, v118
	v_fmac_f32_e32 v127, v128, v128
	v_fmac_f32_e32 v201, v120, v120
	v_pk_add_f32 v[122:123], v[122:123], v[220:221]
	v_fmac_f32_e32 v127, v129, v129
	v_fmac_f32_e32 v201, v121, v121
	v_fmac_f32_e32 v127, v122, v122
	v_fmac_f32_e32 v201, v218, v218
	v_pk_add_f32 v[124:125], v[124:125], v[222:223]
	v_pk_add_f32 v[216:217], v[116:117], v[230:231]
	v_fmac_f32_e32 v127, v123, v123
	v_fmac_f32_e32 v201, v219, v219
	v_fmac_f32_e32 v127, v124, v124
	v_fmac_f32_e32 v201, v216, v216
	v_fmac_f32_e32 v127, v125, v125
	v_fmac_f32_e32 v201, v217, v217
	v_cvt_pk_bf16_f32 v117, v124, v125
	v_add_f32_e32 v124, v127, v201
	ds_bpermute_b32 v125, v187, v124
	v_cvt_pk_bf16_f32 v116, v122, v123
	v_lshl_add_u64 v[122:123], s[26:27], 0, v[232:233]
	v_cvt_pk_bf16_f32 v115, v128, v129
	v_lshl_add_u64 v[122:123], v[196:197], 1, v[122:123]
	global_store_dwordx4 v[122:123], v[114:117], off
	s_waitcnt lgkmcnt(0)
	s_nop 0
	v_add_f32_e32 v114, v124, v125
	ds_bpermute_b32 v115, v189, v114
	v_cvt_pk_bf16_f32 v116, v118, v119
	v_cvt_pk_bf16_f32 v117, v120, v121
	v_cvt_pk_bf16_f32 v118, v218, v219
	v_cvt_pk_bf16_f32 v119, v216, v217
	global_store_dwordx4 v[122:123], v[116:119], off offset:256
	s_and_saveexec_b64 s[14:15], vcc
	s_cbranch_execz .LBB0_533
	s_waitcnt lgkmcnt(0)
	v_add_f32_e32 v114, v114, v115
	v_lshl_add_u32 v115, v214, 2, 0
	v_add_u32_e32 v115, 0x20000, v115
	ds_add_f32 v115, v114

.LBB0_553:
	s_add_i32 s72, s41, 1
	s_cmp_lt_u32 s41, 3
	s_cselect_b64 s[74:75], -1, 0
	s_and_b64 s[38:39], s[74:75], exec
	s_cselect_b32 s38, s72, s40
	ds_read_b128 v[44:47], v39
	ds_read_b128 v[48:51], v39 offset:1024
	ds_read_b128 v[52:55], v39 offset:2048
	ds_read_b128 v[56:59], v39 offset:3072
	s_ashr_i32 s39, s38, 31
	s_lshl_b64 s[38:39], s[38:39], 17
	s_add_u32 s38, s84, s38
	s_addc_u32 s39, s85, s39
	s_and_b64 s[40:41], s[74:75], exec
	s_cselect_b32 s41, s39, s43
	s_cselect_b32 s40, s38, s42
	s_mov_b32 m0, s58
	ds_read_b128 v[60:63], v40
	ds_read_b128 v[64:67], v40 offset:1024
	ds_read_b128 v[68:71], v40 offset:2048
	ds_read_b128 v[72:75], v40 offset:3072
	ds_read_b128 v[76:79], v40 offset:4096
	ds_read_b128 v[80:83], v40 offset:5120
	ds_read_b128 v[84:87], v40 offset:6144
	ds_read_b128 v[88:91], v40 offset:7168
	global_load_lds_dwordx4 v[18:19], off
	s_mov_b32 m0, s59
	s_nop 0
	global_load_lds_dwordx4 v[20:21], off
	s_waitcnt lgkmcnt(8)
	s_barrier
	s_waitcnt lgkmcnt(0)
	s_waitcnt lgkmcnt(0)
	v_mfma_f32_16x16x32_bf16 v[92:95], v[44:47], v[60:63], 0
	v_mfma_f32_16x16x32_bf16 v[96:99], v[52:55], v[60:63], 0
	v_mfma_f32_16x16x32_bf16 v[100:103], v[44:47], v[68:71], 0
	v_mfma_f32_16x16x32_bf16 v[104:107], v[52:55], v[68:71], 0
	v_mfma_f32_16x16x32_bf16 v[108:111], v[44:47], v[76:79], 0
	v_mfma_f32_16x16x32_bf16 v[112:115], v[52:55], v[76:79], 0
	v_mfma_f32_16x16x32_bf16 v[116:119], v[44:47], v[84:87], 0
	v_mfma_f32_16x16x32_bf16 v[120:123], v[52:55], v[84:87], 0
	v_mfma_f32_16x16x32_bf16 v[92:95], v[48:51], v[64:67], v[92:95]
	v_mfma_f32_16x16x32_bf16 v[96:99], v[56:59], v[64:67], v[96:99]
	v_mfma_f32_16x16x32_bf16 v[100:103], v[48:51], v[72:75], v[100:103]
	v_mfma_f32_16x16x32_bf16 v[104:107], v[56:59], v[72:75], v[104:107]
	v_mfma_f32_16x16x32_bf16 v[108:111], v[48:51], v[80:83], v[108:111]
	v_mfma_f32_16x16x32_bf16 v[112:115], v[56:59], v[80:83], v[112:115]
	v_mfma_f32_16x16x32_bf16 v[116:119], v[48:51], v[88:91], v[116:119]
	v_mfma_f32_16x16x32_bf16 v[120:123], v[56:59], v[88:91], v[120:123]
	s_barrier
	v_lshl_add_u64 v[242:243], s[42:43], 0, v[4:5]
	s_mov_b32 m0, s60
	v_lshl_add_u64 v[140:141], v[242:243], 0, s[12:13]
	v_lshl_add_u64 v[244:245], s[42:43], 0, v[2:3]
	ds_read_b128 v[124:127], v41
	ds_read_b128 v[128:131], v41 offset:1024
	ds_read_b128 v[132:135], v41 offset:2048
	ds_read_b128 v[136:139], v41 offset:3072
	global_load_lds_dwordx4 v[140:141], off
	v_lshl_add_u64 v[140:141], v[244:245], 0, s[12:13]
	s_mov_b32 m0, s61
	s_nop 0
	global_load_lds_dwordx4 v[140:141], off
	s_barrier
	s_waitcnt lgkmcnt(0)
	s_waitcnt lgkmcnt(0)
	v_mfma_f32_16x16x32_bf16 v[140:143], v[124:127], v[60:63], 0
	v_mfma_f32_16x16x32_bf16 v[60:63], v[132:135], v[60:63], 0
	v_mfma_f32_16x16x32_bf16 v[140:143], v[128:131], v[64:67], v[140:143]
	v_mfma_f32_16x16x32_bf16 v[60:63], v[136:139], v[64:67], v[60:63]
	v_mfma_f32_16x16x32_bf16 v[64:67], v[124:127], v[68:71], 0
	v_mfma_f32_16x16x32_bf16 v[68:71], v[132:135], v[68:71], 0
	v_mfma_f32_16x16x32_bf16 v[64:67], v[128:131], v[72:75], v[64:67]
	v_mfma_f32_16x16x32_bf16 v[68:71], v[136:139], v[72:75], v[68:71]
	v_mfma_f32_16x16x32_bf16 v[72:75], v[124:127], v[76:79], 0
	v_mfma_f32_16x16x32_bf16 v[76:79], v[132:135], v[76:79], 0
	v_mfma_f32_16x16x32_bf16 v[72:75], v[128:131], v[80:83], v[72:75]
	v_mfma_f32_16x16x32_bf16 v[76:79], v[136:139], v[80:83], v[76:79]
	v_mfma_f32_16x16x32_bf16 v[80:83], v[124:127], v[84:87], 0
	v_mfma_f32_16x16x32_bf16 v[84:87], v[132:135], v[84:87], 0
	v_mfma_f32_16x16x32_bf16 v[80:83], v[128:131], v[88:91], v[80:83]
	v_mfma_f32_16x16x32_bf16 v[84:87], v[136:139], v[88:91], v[84:87]
	s_mov_b32 m0, s3
	s_barrier
	ds_read_b128 v[88:91], v40 offset:16384
	ds_read_b128 v[144:147], v40 offset:17408
	ds_read_b128 v[148:151], v40 offset:18432
	ds_read_b128 v[152:155], v40 offset:19456
	ds_read_b128 v[156:159], v40 offset:20480
	ds_read_b128 v[160:163], v40 offset:21504
	ds_read_b128 v[164:167], v40 offset:22528
	ds_read_b128 v[168:171], v40 offset:23552
	global_load_lds_dwordx4 v[22:23], off
	s_mov_b32 m0, s49
	s_nop 0
	global_load_lds_dwordx4 v[24:25], off
	s_barrier
	s_waitcnt lgkmcnt(0)
	s_waitcnt lgkmcnt(0)
	v_mfma_f32_16x16x32_bf16 v[172:175], v[44:47], v[88:91], 0
	v_mfma_f32_16x16x32_bf16 v[180:183], v[44:47], v[148:151], 0
	v_mfma_f32_16x16x32_bf16 v[194:197], v[44:47], v[156:159], 0
	v_mfma_f32_16x16x32_bf16 v[44:47], v[44:47], v[164:167], 0
	v_mfma_f32_16x16x32_bf16 v[172:175], v[48:51], v[144:147], v[172:175]
	v_mfma_f32_16x16x32_bf16 v[176:179], v[52:55], v[88:91], 0
	v_mfma_f32_16x16x32_bf16 v[180:183], v[48:51], v[152:155], v[180:183]
	v_mfma_f32_16x16x32_bf16 v[190:193], v[52:55], v[148:151], 0
	v_mfma_f32_16x16x32_bf16 v[194:197], v[48:51], v[160:163], v[194:197]
	v_mfma_f32_16x16x32_bf16 v[198:201], v[52:55], v[156:159], 0
	v_mfma_f32_16x16x32_bf16 v[44:47], v[48:51], v[168:171], v[44:47]
	v_mfma_f32_16x16x32_bf16 v[48:51], v[52:55], v[164:167], 0
	v_mfma_f32_16x16x32_bf16 v[176:179], v[56:59], v[144:147], v[176:179]
	v_mfma_f32_16x16x32_bf16 v[190:193], v[56:59], v[152:155], v[190:193]
	v_mfma_f32_16x16x32_bf16 v[198:201], v[56:59], v[160:163], v[198:201]
	v_mfma_f32_16x16x32_bf16 v[48:51], v[56:59], v[168:171], v[48:51]
	s_barrier
	s_add_u32 s74, s42, 0x10100
	s_addc_u32 s75, s43, 0
	s_mov_b32 m0, s62
	v_lshl_add_u64 v[52:53], s[74:75], 0, v[4:5]
	global_load_lds_dwordx4 v[52:53], off
	v_lshl_add_u64 v[52:53], s[74:75], 0, v[2:3]
	s_mov_b32 m0, s63
	s_nop 0
	global_load_lds_dwordx4 v[52:53], off
	s_waitcnt vmcnt(6)
	s_barrier
	v_mfma_f32_16x16x32_bf16 v[52:55], v[124:127], v[88:91], 0
	v_mfma_f32_16x16x32_bf16 v[56:59], v[132:135], v[88:91], 0
	v_mfma_f32_16x16x32_bf16 v[52:55], v[128:131], v[144:147], v[52:55]
	v_mfma_f32_16x16x32_bf16 v[56:59], v[136:139], v[144:147], v[56:59]
	v_mfma_f32_16x16x32_bf16 v[88:91], v[124:127], v[148:151], 0
	v_mfma_f32_16x16x32_bf16 v[144:147], v[132:135], v[148:151], 0
	v_mfma_f32_16x16x32_bf16 v[148:151], v[124:127], v[156:159], 0
	v_mfma_f32_16x16x32_bf16 v[124:127], v[124:127], v[164:167], 0
	v_mfma_f32_16x16x32_bf16 v[88:91], v[128:131], v[152:155], v[88:91]
	v_mfma_f32_16x16x32_bf16 v[144:147], v[136:139], v[152:155], v[144:147]
	v_mfma_f32_16x16x32_bf16 v[148:151], v[128:131], v[160:163], v[148:151]
	v_mfma_f32_16x16x32_bf16 v[152:155], v[132:135], v[156:159], 0
	v_mfma_f32_16x16x32_bf16 v[124:127], v[128:131], v[168:171], v[124:127]
	v_mfma_f32_16x16x32_bf16 v[128:131], v[132:135], v[164:167], 0
	v_mfma_f32_16x16x32_bf16 v[152:155], v[136:139], v[160:163], v[152:155]
	v_mfma_f32_16x16x32_bf16 v[128:131], v[136:139], v[168:171], v[128:131]
	s_barrier
	ds_read_b128 v[132:135], v42
	ds_read_b128 v[136:139], v42 offset:1024
	ds_read_b128 v[156:159], v42 offset:2048
	ds_read_b128 v[160:163], v42 offset:3072
	s_mov_b32 m0, s50
	ds_read_b128 v[164:167], v40 offset:32768
	ds_read_b128 v[168:171], v40 offset:33792
	ds_read_b128 v[202:205], v40 offset:34816
	ds_read_b128 v[206:209], v40 offset:35840
	ds_read_b128 v[210:213], v40 offset:36864
	ds_read_b128 v[214:217], v40 offset:37888
	ds_read_b128 v[218:221], v40 offset:38912
	ds_read_b128 v[222:225], v40 offset:39936
	global_load_lds_dwordx4 v[26:27], off
	s_mov_b32 m0, s51
	s_nop 0
	global_load_lds_dwordx4 v[28:29], off
	s_waitcnt lgkmcnt(8)
	s_barrier
	s_waitcnt lgkmcnt(0)
	s_waitcnt lgkmcnt(0)
	v_mfma_f32_16x16x32_bf16 v[92:95], v[132:135], v[164:167], v[92:95]
	v_mfma_f32_16x16x32_bf16 v[96:99], v[156:159], v[164:167], v[96:99]
	v_mfma_f32_16x16x32_bf16 v[100:103], v[132:135], v[202:205], v[100:103]
	v_mfma_f32_16x16x32_bf16 v[104:107], v[156:159], v[202:205], v[104:107]
	v_mfma_f32_16x16x32_bf16 v[108:111], v[132:135], v[210:213], v[108:111]
	v_mfma_f32_16x16x32_bf16 v[112:115], v[156:159], v[210:213], v[112:115]
	v_mfma_f32_16x16x32_bf16 v[116:119], v[132:135], v[218:221], v[116:119]
	v_mfma_f32_16x16x32_bf16 v[120:123], v[156:159], v[218:221], v[120:123]
	v_mfma_f32_16x16x32_bf16 v[92:95], v[136:139], v[168:171], v[92:95]
	v_mfma_f32_16x16x32_bf16 v[96:99], v[160:163], v[168:171], v[96:99]
	v_mfma_f32_16x16x32_bf16 v[100:103], v[136:139], v[206:209], v[100:103]
	v_mfma_f32_16x16x32_bf16 v[104:107], v[160:163], v[206:209], v[104:107]
	v_mfma_f32_16x16x32_bf16 v[108:111], v[136:139], v[214:217], v[108:111]
	v_mfma_f32_16x16x32_bf16 v[112:115], v[160:163], v[214:217], v[112:115]
	v_mfma_f32_16x16x32_bf16 v[116:119], v[136:139], v[222:225], v[116:119]
	v_mfma_f32_16x16x32_bf16 v[120:123], v[160:163], v[222:225], v[120:123]
	s_barrier
	s_mov_b32 m0, s64
	v_lshl_add_u64 v[242:243], v[242:243], 0, s[14:15]
	ds_read_b128 v[226:229], v43
	ds_read_b128 v[230:233], v43 offset:1024
	ds_read_b128 v[234:237], v43 offset:2048
	ds_read_b128 v[238:241], v43 offset:3072
	global_load_lds_dwordx4 v[242:243], off
	v_lshl_add_u64 v[242:243], v[244:245], 0, s[14:15]
	s_mov_b32 m0, s65
	s_nop 0
	global_load_lds_dwordx4 v[242:243], off
	s_barrier
	s_waitcnt lgkmcnt(0)
	s_waitcnt lgkmcnt(0)
	v_mfma_f32_16x16x32_bf16 v[140:143], v[226:229], v[164:167], v[140:143]
	v_mfma_f32_16x16x32_bf16 v[60:63], v[234:237], v[164:167], v[60:63]
	v_mfma_f32_16x16x32_bf16 v[64:67], v[226:229], v[202:205], v[64:67]
	v_mfma_f32_16x16x32_bf16 v[68:71], v[234:237], v[202:205], v[68:71]
	v_mfma_f32_16x16x32_bf16 v[72:75], v[226:229], v[210:213], v[72:75]
	v_mfma_f32_16x16x32_bf16 v[76:79], v[234:237], v[210:213], v[76:79]
	v_mfma_f32_16x16x32_bf16 v[80:83], v[226:229], v[218:221], v[80:83]
	v_mfma_f32_16x16x32_bf16 v[84:87], v[234:237], v[218:221], v[84:87]
	v_mfma_f32_16x16x32_bf16 v[140:143], v[230:233], v[168:171], v[140:143]
	v_mfma_f32_16x16x32_bf16 v[60:63], v[238:241], v[168:171], v[60:63]
	v_mfma_f32_16x16x32_bf16 v[64:67], v[230:233], v[206:209], v[64:67]
	v_mfma_f32_16x16x32_bf16 v[68:71], v[238:241], v[206:209], v[68:71]
	v_mfma_f32_16x16x32_bf16 v[72:75], v[230:233], v[214:217], v[72:75]
	v_mfma_f32_16x16x32_bf16 v[76:79], v[238:241], v[214:217], v[76:79]
	v_mfma_f32_16x16x32_bf16 v[80:83], v[230:233], v[222:225], v[80:83]
	v_mfma_f32_16x16x32_bf16 v[84:87], v[238:241], v[222:225], v[84:87]
	s_mov_b32 m0, s53
	s_barrier
	ds_read_b128 v[164:167], v40 offset:49152
	ds_read_b128 v[168:171], v40 offset:50176
	ds_read_b128 v[202:205], v40 offset:51200
	ds_read_b128 v[206:209], v40 offset:52224
	ds_read_b128 v[210:213], v40 offset:53248
	ds_read_b128 v[214:217], v40 offset:54272
	ds_read_b128 v[218:221], v40 offset:55296
	ds_read_b128 v[222:225], v40 offset:56320
	global_load_lds_dwordx4 v[30:31], off
	s_mov_b32 m0, s54
	s_nop 0
	global_load_lds_dwordx4 v[32:33], off
	s_barrier
	s_waitcnt lgkmcnt(0)
	s_waitcnt lgkmcnt(0)
	v_mfma_f32_16x16x32_bf16 v[172:175], v[132:135], v[164:167], v[172:175]
	v_mfma_f32_16x16x32_bf16 v[176:179], v[156:159], v[164:167], v[176:179]
	v_mfma_f32_16x16x32_bf16 v[180:183], v[132:135], v[202:205], v[180:183]
	v_mfma_f32_16x16x32_bf16 v[190:193], v[156:159], v[202:205], v[190:193]
	v_mfma_f32_16x16x32_bf16 v[194:197], v[132:135], v[210:213], v[194:197]
	v_mfma_f32_16x16x32_bf16 v[198:201], v[156:159], v[210:213], v[198:201]
	v_mfma_f32_16x16x32_bf16 v[44:47], v[132:135], v[218:221], v[44:47]
	v_mfma_f32_16x16x32_bf16 v[48:51], v[156:159], v[218:221], v[48:51]
	v_mfma_f32_16x16x32_bf16 v[172:175], v[136:139], v[168:171], v[172:175]
	v_mfma_f32_16x16x32_bf16 v[176:179], v[160:163], v[168:171], v[176:179]
	v_mfma_f32_16x16x32_bf16 v[180:183], v[136:139], v[206:209], v[180:183]
	v_mfma_f32_16x16x32_bf16 v[190:193], v[160:163], v[206:209], v[190:193]
	v_mfma_f32_16x16x32_bf16 v[194:197], v[136:139], v[214:217], v[194:197]
	v_mfma_f32_16x16x32_bf16 v[198:201], v[160:163], v[214:217], v[198:201]
	v_mfma_f32_16x16x32_bf16 v[44:47], v[136:139], v[222:225], v[44:47]
	v_mfma_f32_16x16x32_bf16 v[48:51], v[160:163], v[222:225], v[48:51]
	s_barrier
	s_add_u32 s42, s42, 0x10180
	s_addc_u32 s43, s43, 0
	s_mov_b32 m0, s66
	v_lshl_add_u64 v[132:133], s[42:43], 0, v[4:5]
	global_load_lds_dwordx4 v[132:133], off
	v_lshl_add_u64 v[132:133], s[42:43], 0, v[2:3]
	s_mov_b32 m0, s67
	s_nop 0
	global_load_lds_dwordx4 v[132:133], off
	s_waitcnt vmcnt(6)
	s_barrier
	v_mfma_f32_16x16x32_bf16 v[52:55], v[226:229], v[164:167], v[52:55]
	v_mfma_f32_16x16x32_bf16 v[56:59], v[234:237], v[164:167], v[56:59]
	v_mfma_f32_16x16x32_bf16 v[88:91], v[226:229], v[202:205], v[88:91]
	v_mfma_f32_16x16x32_bf16 v[132:135], v[234:237], v[202:205], v[144:147]
	v_mfma_f32_16x16x32_bf16 v[136:139], v[226:229], v[210:213], v[148:151]
	v_mfma_f32_16x16x32_bf16 v[144:147], v[234:237], v[210:213], v[152:155]
	v_mfma_f32_16x16x32_bf16 v[124:127], v[226:229], v[218:221], v[124:127]
	v_mfma_f32_16x16x32_bf16 v[128:131], v[234:237], v[218:221], v[128:131]
	v_mfma_f32_16x16x32_bf16 v[52:55], v[230:233], v[168:171], v[52:55]
	v_mfma_f32_16x16x32_bf16 v[56:59], v[238:241], v[168:171], v[56:59]
	v_mfma_f32_16x16x32_bf16 v[88:91], v[230:233], v[206:209], v[88:91]
	v_mfma_f32_16x16x32_bf16 v[132:135], v[238:241], v[206:209], v[132:135]
	v_mfma_f32_16x16x32_bf16 v[136:139], v[230:233], v[214:217], v[136:139]
	v_mfma_f32_16x16x32_bf16 v[144:147], v[238:241], v[214:217], v[144:147]
	v_mfma_f32_16x16x32_bf16 v[124:127], v[230:233], v[222:225], v[124:127]
	v_mfma_f32_16x16x32_bf16 v[128:131], v[238:241], v[222:225], v[128:131]
	s_barrier
	ds_read_b128 v[148:151], v39
	ds_read_b128 v[152:155], v39 offset:1024
	ds_read_b128 v[156:159], v39 offset:2048
	ds_read_b128 v[160:163], v39 offset:3072
	s_mov_b32 m0, s58
	ds_read_b128 v[164:167], v40
	ds_read_b128 v[168:171], v40 offset:1024
	ds_read_b128 v[202:205], v40 offset:2048
	ds_read_b128 v[206:209], v40 offset:3072
	ds_read_b128 v[210:213], v40 offset:4096
	ds_read_b128 v[214:217], v40 offset:5120
	ds_read_b128 v[218:221], v40 offset:6144
	ds_read_b128 v[222:225], v40 offset:7168
	global_load_lds_dwordx4 v[34:35], off
	s_mov_b32 m0, s59
	s_nop 0
	global_load_lds_dwordx4 v[36:37], off
	s_waitcnt lgkmcnt(8)
	s_barrier
	s_waitcnt lgkmcnt(0)
	s_waitcnt lgkmcnt(0)
	v_mfma_f32_16x16x32_bf16 v[92:95], v[148:151], v[164:167], v[92:95]
	v_mfma_f32_16x16x32_bf16 v[96:99], v[156:159], v[164:167], v[96:99]
	v_mfma_f32_16x16x32_bf16 v[100:103], v[148:151], v[202:205], v[100:103]
	v_mfma_f32_16x16x32_bf16 v[104:107], v[156:159], v[202:205], v[104:107]
	v_mfma_f32_16x16x32_bf16 v[108:111], v[148:151], v[210:213], v[108:111]
	v_mfma_f32_16x16x32_bf16 v[112:115], v[156:159], v[210:213], v[112:115]
	v_mfma_f32_16x16x32_bf16 v[116:119], v[148:151], v[218:221], v[116:119]
	v_mfma_f32_16x16x32_bf16 v[120:123], v[156:159], v[218:221], v[120:123]
	v_mfma_f32_16x16x32_bf16 v[92:95], v[152:155], v[168:171], v[92:95]
	v_mfma_f32_16x16x32_bf16 v[96:99], v[160:163], v[168:171], v[96:99]
	v_mfma_f32_16x16x32_bf16 v[100:103], v[152:155], v[206:209], v[100:103]
	v_mfma_f32_16x16x32_bf16 v[104:107], v[160:163], v[206:209], v[104:107]
	v_mfma_f32_16x16x32_bf16 v[108:111], v[152:155], v[214:217], v[108:111]
	v_mfma_f32_16x16x32_bf16 v[112:115], v[160:163], v[214:217], v[112:115]
	v_mfma_f32_16x16x32_bf16 v[116:119], v[152:155], v[222:225], v[116:119]
	v_mfma_f32_16x16x32_bf16 v[120:123], v[160:163], v[222:225], v[120:123]
	s_barrier
	s_mov_b32 m0, s60
	v_lshl_add_u64 v[242:243], s[40:41], 0, v[4:5]
	ds_read_b128 v[226:229], v41
	ds_read_b128 v[230:233], v41 offset:1024
	ds_read_b128 v[234:237], v41 offset:2048
	ds_read_b128 v[238:241], v41 offset:3072
	global_load_lds_dwordx4 v[242:243], off
	v_lshl_add_u64 v[244:245], s[40:41], 0, v[2:3]
	s_mov_b32 m0, s61
	s_nop 0
	global_load_lds_dwordx4 v[244:245], off
	s_barrier
	s_waitcnt lgkmcnt(0)
	s_waitcnt lgkmcnt(0)
	v_mfma_f32_16x16x32_bf16 v[140:143], v[226:229], v[164:167], v[140:143]
	v_mfma_f32_16x16x32_bf16 v[60:63], v[234:237], v[164:167], v[60:63]
	v_mfma_f32_16x16x32_bf16 v[64:67], v[226:229], v[202:205], v[64:67]
	v_mfma_f32_16x16x32_bf16 v[68:71], v[234:237], v[202:205], v[68:71]
	v_mfma_f32_16x16x32_bf16 v[72:75], v[226:229], v[210:213], v[72:75]
	v_mfma_f32_16x16x32_bf16 v[76:79], v[234:237], v[210:213], v[76:79]
	v_mfma_f32_16x16x32_bf16 v[80:83], v[226:229], v[218:221], v[80:83]
	v_mfma_f32_16x16x32_bf16 v[84:87], v[234:237], v[218:221], v[84:87]
	v_mfma_f32_16x16x32_bf16 v[140:143], v[230:233], v[168:171], v[140:143]
	v_mfma_f32_16x16x32_bf16 v[60:63], v[238:241], v[168:171], v[60:63]
	v_mfma_f32_16x16x32_bf16 v[64:67], v[230:233], v[206:209], v[64:67]
	v_mfma_f32_16x16x32_bf16 v[68:71], v[238:241], v[206:209], v[68:71]
	v_mfma_f32_16x16x32_bf16 v[72:75], v[230:233], v[214:217], v[72:75]
	v_mfma_f32_16x16x32_bf16 v[76:79], v[238:241], v[214:217], v[76:79]
	v_mfma_f32_16x16x32_bf16 v[80:83], v[230:233], v[222:225], v[80:83]
	v_mfma_f32_16x16x32_bf16 v[84:87], v[238:241], v[222:225], v[84:87]
	s_mov_b32 m0, s3
	s_barrier
	ds_read_b128 v[164:167], v40 offset:16384
	ds_read_b128 v[168:171], v40 offset:17408
	ds_read_b128 v[202:205], v40 offset:18432
	ds_read_b128 v[206:209], v40 offset:19456
	ds_read_b128 v[210:213], v40 offset:20480
	ds_read_b128 v[214:217], v40 offset:21504
	ds_read_b128 v[218:221], v40 offset:22528
	ds_read_b128 v[222:225], v40 offset:23552
	global_load_lds_dwordx4 v[6:7], off
	s_mov_b32 m0, s49
	s_nop 0
	global_load_lds_dwordx4 v[8:9], off
	s_barrier
	s_waitcnt lgkmcnt(0)
	s_waitcnt lgkmcnt(0)
	v_mfma_f32_16x16x32_bf16 v[172:175], v[148:151], v[164:167], v[172:175]
	v_mfma_f32_16x16x32_bf16 v[176:179], v[156:159], v[164:167], v[176:179]
	v_mfma_f32_16x16x32_bf16 v[180:183], v[148:151], v[202:205], v[180:183]
	v_mfma_f32_16x16x32_bf16 v[190:193], v[156:159], v[202:205], v[190:193]
	v_mfma_f32_16x16x32_bf16 v[194:197], v[148:151], v[210:213], v[194:197]
	v_mfma_f32_16x16x32_bf16 v[198:201], v[156:159], v[210:213], v[198:201]
	v_mfma_f32_16x16x32_bf16 v[44:47], v[148:151], v[218:221], v[44:47]
	v_mfma_f32_16x16x32_bf16 v[48:51], v[156:159], v[218:221], v[48:51]
	v_mfma_f32_16x16x32_bf16 v[172:175], v[152:155], v[168:171], v[172:175]
	v_mfma_f32_16x16x32_bf16 v[176:179], v[160:163], v[168:171], v[176:179]
	v_mfma_f32_16x16x32_bf16 v[180:183], v[152:155], v[206:209], v[180:183]
	v_mfma_f32_16x16x32_bf16 v[190:193], v[160:163], v[206:209], v[190:193]
	v_mfma_f32_16x16x32_bf16 v[194:197], v[152:155], v[214:217], v[194:197]
	v_mfma_f32_16x16x32_bf16 v[198:201], v[160:163], v[214:217], v[198:201]
	v_mfma_f32_16x16x32_bf16 v[44:47], v[152:155], v[222:225], v[44:47]
	v_mfma_f32_16x16x32_bf16 v[48:51], v[160:163], v[222:225], v[48:51]
	s_barrier
	s_add_u32 s42, s40, 0x10000
	s_addc_u32 s43, s41, 0
	s_mov_b32 m0, s62
	v_lshl_add_u64 v[148:149], s[42:43], 0, v[4:5]
	global_load_lds_dwordx4 v[148:149], off
	v_lshl_add_u64 v[148:149], s[42:43], 0, v[2:3]
	s_mov_b32 m0, s63
	s_nop 0
	global_load_lds_dwordx4 v[148:149], off
	s_waitcnt vmcnt(6)
	s_barrier
	v_mfma_f32_16x16x32_bf16 v[52:55], v[226:229], v[164:167], v[52:55]
	v_mfma_f32_16x16x32_bf16 v[56:59], v[234:237], v[164:167], v[56:59]
	v_mfma_f32_16x16x32_bf16 v[88:91], v[226:229], v[202:205], v[88:91]
	v_mfma_f32_16x16x32_bf16 v[132:135], v[234:237], v[202:205], v[132:135]
	v_mfma_f32_16x16x32_bf16 v[136:139], v[226:229], v[210:213], v[136:139]
	v_mfma_f32_16x16x32_bf16 v[144:147], v[234:237], v[210:213], v[144:147]
	v_mfma_f32_16x16x32_bf16 v[124:127], v[226:229], v[218:221], v[124:127]
	v_mfma_f32_16x16x32_bf16 v[128:131], v[234:237], v[218:221], v[128:131]
	v_mfma_f32_16x16x32_bf16 v[52:55], v[230:233], v[168:171], v[52:55]
	v_mfma_f32_16x16x32_bf16 v[56:59], v[238:241], v[168:171], v[56:59]
	v_mfma_f32_16x16x32_bf16 v[88:91], v[230:233], v[206:209], v[88:91]
	v_mfma_f32_16x16x32_bf16 v[132:135], v[238:241], v[206:209], v[132:135]
	v_mfma_f32_16x16x32_bf16 v[136:139], v[230:233], v[214:217], v[136:139]
	v_mfma_f32_16x16x32_bf16 v[144:147], v[238:241], v[214:217], v[144:147]
	v_mfma_f32_16x16x32_bf16 v[124:127], v[230:233], v[222:225], v[124:127]
	v_mfma_f32_16x16x32_bf16 v[128:131], v[238:241], v[222:225], v[128:131]
	s_barrier
	ds_read_b128 v[148:151], v42
	ds_read_b128 v[152:155], v42 offset:1024
	ds_read_b128 v[156:159], v42 offset:2048
	ds_read_b128 v[160:163], v42 offset:3072
	s_mov_b32 m0, s50
	ds_read_b128 v[164:167], v40 offset:32768
	ds_read_b128 v[168:171], v40 offset:33792
	ds_read_b128 v[202:205], v40 offset:34816
	ds_read_b128 v[206:209], v40 offset:35840
	ds_read_b128 v[210:213], v40 offset:36864
	ds_read_b128 v[214:217], v40 offset:37888
	ds_read_b128 v[218:221], v40 offset:38912
	ds_read_b128 v[222:225], v40 offset:39936
	global_load_lds_dwordx4 v[14:15], off
	s_mov_b32 m0, s51
	s_nop 0
	global_load_lds_dwordx4 v[16:17], off
	s_waitcnt lgkmcnt(8)
	s_barrier
	s_waitcnt lgkmcnt(0)
	s_waitcnt lgkmcnt(0)
	v_mfma_f32_16x16x32_bf16 v[92:95], v[148:151], v[164:167], v[92:95]
	v_mfma_f32_16x16x32_bf16 v[96:99], v[156:159], v[164:167], v[96:99]
	v_mfma_f32_16x16x32_bf16 v[100:103], v[148:151], v[202:205], v[100:103]
	v_mfma_f32_16x16x32_bf16 v[104:107], v[156:159], v[202:205], v[104:107]
	v_mfma_f32_16x16x32_bf16 v[108:111], v[148:151], v[210:213], v[108:111]
	v_mfma_f32_16x16x32_bf16 v[112:115], v[156:159], v[210:213], v[112:115]
	v_mfma_f32_16x16x32_bf16 v[116:119], v[148:151], v[218:221], v[116:119]
	v_mfma_f32_16x16x32_bf16 v[120:123], v[156:159], v[218:221], v[120:123]
	v_mfma_f32_16x16x32_bf16 v[92:95], v[152:155], v[168:171], v[92:95]
	v_mfma_f32_16x16x32_bf16 v[96:99], v[160:163], v[168:171], v[96:99]
	v_mfma_f32_16x16x32_bf16 v[100:103], v[152:155], v[206:209], v[100:103]
	v_mfma_f32_16x16x32_bf16 v[104:107], v[160:163], v[206:209], v[104:107]
	v_mfma_f32_16x16x32_bf16 v[108:111], v[152:155], v[214:217], v[108:111]
	v_mfma_f32_16x16x32_bf16 v[112:115], v[160:163], v[214:217], v[112:115]
	v_mfma_f32_16x16x32_bf16 v[116:119], v[152:155], v[222:225], v[116:119]
	v_mfma_f32_16x16x32_bf16 v[120:123], v[160:163], v[222:225], v[120:123]
	s_barrier
	s_mov_b32 m0, s64
	v_lshl_add_u64 v[242:243], v[242:243], 0, s[0:1]
	ds_read_b128 v[226:229], v43
	ds_read_b128 v[230:233], v43 offset:1024
	ds_read_b128 v[234:237], v43 offset:2048
	ds_read_b128 v[238:241], v43 offset:3072
	global_load_lds_dwordx4 v[242:243], off
	v_lshl_add_u64 v[242:243], v[244:245], 0, s[0:1]
	s_mov_b32 m0, s65
	s_nop 0
	global_load_lds_dwordx4 v[242:243], off
	s_barrier
	s_waitcnt lgkmcnt(0)
	s_waitcnt lgkmcnt(0)
	v_mfma_f32_16x16x32_bf16 v[140:143], v[226:229], v[164:167], v[140:143]
	v_mfma_f32_16x16x32_bf16 v[60:63], v[234:237], v[164:167], v[60:63]
	v_mfma_f32_16x16x32_bf16 v[64:67], v[226:229], v[202:205], v[64:67]
	v_mfma_f32_16x16x32_bf16 v[68:71], v[234:237], v[202:205], v[68:71]
	v_mfma_f32_16x16x32_bf16 v[72:75], v[226:229], v[210:213], v[72:75]
	v_mfma_f32_16x16x32_bf16 v[76:79], v[234:237], v[210:213], v[76:79]
	v_mfma_f32_16x16x32_bf16 v[80:83], v[226:229], v[218:221], v[80:83]
	v_mfma_f32_16x16x32_bf16 v[84:87], v[234:237], v[218:221], v[84:87]
	v_mfma_f32_16x16x32_bf16 v[140:143], v[230:233], v[168:171], v[140:143]
	v_mfma_f32_16x16x32_bf16 v[60:63], v[238:241], v[168:171], v[60:63]
	v_mfma_f32_16x16x32_bf16 v[64:67], v[230:233], v[206:209], v[64:67]
	v_mfma_f32_16x16x32_bf16 v[68:71], v[238:241], v[206:209], v[68:71]
	v_mfma_f32_16x16x32_bf16 v[72:75], v[230:233], v[214:217], v[72:75]
	v_mfma_f32_16x16x32_bf16 v[76:79], v[238:241], v[214:217], v[76:79]
	v_mfma_f32_16x16x32_bf16 v[80:83], v[230:233], v[222:225], v[80:83]
	v_mfma_f32_16x16x32_bf16 v[84:87], v[238:241], v[222:225], v[84:87]
	s_mov_b32 m0, s53
	s_barrier
	ds_read_b128 v[164:167], v40 offset:49152
	ds_read_b128 v[168:171], v40 offset:50176
	ds_read_b128 v[202:205], v40 offset:51200
	ds_read_b128 v[206:209], v40 offset:52224
	ds_read_b128 v[210:213], v40 offset:53248
	ds_read_b128 v[214:217], v40 offset:54272
	ds_read_b128 v[218:221], v40 offset:55296
	ds_read_b128 v[222:225], v40 offset:56320
	global_load_lds_dwordx4 v[10:11], off
	s_mov_b32 m0, s54
	s_nop 0
	global_load_lds_dwordx4 v[12:13], off
	s_barrier
	s_waitcnt lgkmcnt(0)
	s_waitcnt lgkmcnt(0)
	v_mfma_f32_16x16x32_bf16 v[172:175], v[148:151], v[164:167], v[172:175]
	v_mfma_f32_16x16x32_bf16 v[176:179], v[156:159], v[164:167], v[176:179]
	v_mfma_f32_16x16x32_bf16 v[180:183], v[148:151], v[202:205], v[180:183]
	v_mfma_f32_16x16x32_bf16 v[190:193], v[156:159], v[202:205], v[190:193]
	v_mfma_f32_16x16x32_bf16 v[194:197], v[148:151], v[210:213], v[194:197]
	v_mfma_f32_16x16x32_bf16 v[198:201], v[156:159], v[210:213], v[198:201]
	v_mfma_f32_16x16x32_bf16 v[44:47], v[148:151], v[218:221], v[44:47]
	v_mfma_f32_16x16x32_bf16 v[48:51], v[156:159], v[218:221], v[48:51]
	v_mfma_f32_16x16x32_bf16 v[172:175], v[152:155], v[168:171], v[172:175]
	v_mfma_f32_16x16x32_bf16 v[176:179], v[160:163], v[168:171], v[176:179]
	v_mfma_f32_16x16x32_bf16 v[180:183], v[152:155], v[206:209], v[180:183]
	v_mfma_f32_16x16x32_bf16 v[190:193], v[160:163], v[206:209], v[190:193]
	v_mfma_f32_16x16x32_bf16 v[194:197], v[152:155], v[214:217], v[194:197]
	v_mfma_f32_16x16x32_bf16 v[198:201], v[160:163], v[214:217], v[198:201]
	v_mfma_f32_16x16x32_bf16 v[44:47], v[152:155], v[222:225], v[44:47]
	v_mfma_f32_16x16x32_bf16 v[48:51], v[160:163], v[222:225], v[48:51]
	s_barrier
	s_add_u32 s40, s40, 0x10080
	s_addc_u32 s41, s41, 0
	s_mov_b32 m0, s66
	v_lshl_add_u64 v[148:149], s[40:41], 0, v[4:5]
	global_load_lds_dwordx4 v[148:149], off
	v_lshl_add_u64 v[148:149], s[40:41], 0, v[2:3]
	s_mov_b32 m0, s67
	s_nop 0
	global_load_lds_dwordx4 v[148:149], off
	s_waitcnt vmcnt(6)
	s_barrier
	v_mfma_f32_16x16x32_bf16 v[52:55], v[226:229], v[164:167], v[52:55]
	v_mfma_f32_16x16x32_bf16 v[56:59], v[234:237], v[164:167], v[56:59]
	v_mfma_f32_16x16x32_bf16 v[88:91], v[226:229], v[202:205], v[88:91]
	v_mfma_f32_16x16x32_bf16 v[132:135], v[234:237], v[202:205], v[132:135]
	v_mfma_f32_16x16x32_bf16 v[136:139], v[226:229], v[210:213], v[136:139]
	v_mfma_f32_16x16x32_bf16 v[144:147], v[234:237], v[210:213], v[144:147]
	v_mfma_f32_16x16x32_bf16 v[124:127], v[226:229], v[218:221], v[124:127]
	v_mfma_f32_16x16x32_bf16 v[128:131], v[234:237], v[218:221], v[128:131]
	v_mfma_f32_16x16x32_bf16 v[52:55], v[230:233], v[168:171], v[52:55]
	v_mfma_f32_16x16x32_bf16 v[56:59], v[238:241], v[168:171], v[56:59]
	v_mfma_f32_16x16x32_bf16 v[88:91], v[230:233], v[206:209], v[88:91]
	v_mfma_f32_16x16x32_bf16 v[132:135], v[238:241], v[206:209], v[132:135]
	v_mfma_f32_16x16x32_bf16 v[136:139], v[230:233], v[214:217], v[136:139]
	v_mfma_f32_16x16x32_bf16 v[144:147], v[238:241], v[214:217], v[144:147]
	v_mfma_f32_16x16x32_bf16 v[124:127], v[230:233], v[222:225], v[124:127]
	v_mfma_f32_16x16x32_bf16 v[128:131], v[238:241], v[222:225], v[128:131]
	v_mov_b32_e32 v148, v1
	v_mov_b32_e32 v149, v38
	s_barrier
	v_cvt_pk_bf16_f32 v64, v64, v65
	v_cvt_pk_bf16_f32 v65, v66, v67
	v_cvt_pk_bf16_f32 v66, v68, v69
	v_cvt_pk_bf16_f32 v68, v108, v109
	v_cvt_pk_bf16_f32 v69, v110, v111
	v_add_u32_e32 v108, s57, v148
	v_lshlrev_b32_e32 v110, 3, v149
	v_ashrrev_i32_e32 v109, 31, v108
	v_ashrrev_i32_e32 v111, 31, v110
	v_lshlrev_b64 v[108:109], 11, v[108:109]
	v_lshl_add_u64 v[110:111], s[36:37], 0, v[110:111]
	v_lshl_add_u64 v[108:109], s[24:25], 0, v[108:109]
	v_cvt_pk_bf16_f32 v92, v92, v93
	v_cvt_pk_bf16_f32 v93, v94, v95
	v_cvt_pk_bf16_f32 v94, v96, v97
	v_cvt_pk_bf16_f32 v95, v98, v99
	v_lshl_add_u64 v[108:109], v[110:111], 1, v[108:109]
	v_cvt_pk_bf16_f32 v96, v140, v141
	v_cvt_pk_bf16_f32 v97, v142, v143
	v_cvt_pk_bf16_f32 v98, v60, v61
	v_cvt_pk_bf16_f32 v99, v62, v63
	global_store_dwordx4 v[108:109], v[92:95], off
	global_store_dwordx4 v[108:109], v[96:99], off offset:256
	v_cvt_pk_bf16_f32 v67, v70, v71
	v_add_co_u32_e32 v94, vcc, s56, v108
	v_cvt_pk_bf16_f32 v70, v112, v113
	s_nop 0
	v_addc_co_u32_e32 v95, vcc, 0, v109, vcc
	v_add_co_u32_e32 v98, vcc, s52, v108
	v_cvt_pk_bf16_f32 v72, v72, v73
	s_nop 0
	v_addc_co_u32_e32 v99, vcc, 0, v109, vcc
	v_add_co_u32_e32 v112, vcc, s55, v108
	v_cvt_pk_bf16_f32 v73, v74, v75
	s_nop 0
	v_addc_co_u32_e32 v113, vcc, 0, v109, vcc
	v_cvt_pk_bf16_f32 v74, v76, v77
	v_cvt_pk_bf16_f32 v76, v116, v117
	v_add_co_u32_e32 v116, vcc, s68, v108
	v_cvt_pk_bf16_f32 v75, v78, v79
	s_nop 0
	v_addc_co_u32_e32 v117, vcc, 0, v109, vcc
	v_cvt_pk_bf16_f32 v78, v120, v121
	v_add_co_u32_e32 v120, vcc, s69, v108
	v_cvt_pk_bf16_f32 v44, v44, v45
	s_nop 0
	v_addc_co_u32_e32 v121, vcc, 0, v109, vcc
	v_cvt_pk_bf16_f32 v45, v46, v47
	v_cvt_pk_bf16_f32 v46, v48, v49
	v_cvt_pk_bf16_f32 v48, v124, v125
	s_add_u32 s36, s36, 0x100
	v_add_co_u32_e32 v124, vcc, s70, v108
	s_addc_u32 s37, s37, 0
	s_nop 0
	v_addc_co_u32_e32 v125, vcc, 0, v109, vcc
	v_cvt_pk_bf16_f32 v60, v100, v101
	v_cvt_pk_bf16_f32 v61, v102, v103
	v_cvt_pk_bf16_f32 v62, v104, v105
	v_cvt_pk_bf16_f32 v63, v106, v107
	v_cvt_pk_bf16_f32 v71, v114, v115
	v_cvt_pk_bf16_f32 v77, v118, v119
	v_cvt_pk_bf16_f32 v79, v122, v123
	v_cvt_pk_bf16_f32 v47, v50, v51
	v_cvt_pk_bf16_f32 v49, v126, v127
	v_cvt_pk_bf16_f32 v50, v128, v129
	v_cvt_pk_bf16_f32 v51, v130, v131
	s_mov_b32 s41, s72
	s_mov_b32 s40, s72
	s_mov_b64 s[42:43], s[38:39]
	s_cmp_lg_u32 s72, 4
	v_lshl_add_u64 v[92:93], v[108:109], 0, s[18:19]
	v_lshl_add_u64 v[96:97], v[108:109], 0, s[16:17]
	v_lshl_add_u64 v[110:111], v[108:109], 0, s[20:21]
	v_lshl_add_u64 v[114:115], v[108:109], 0, s[22:23]
	v_lshl_add_u64 v[118:119], v[108:109], 0, s[28:29]
	v_lshl_add_u64 v[122:123], v[108:109], 0, s[30:31]
	v_lshl_add_u64 v[126:127], v[108:109], 0, s[34:35]
	v_add_co_u32_e32 v108, vcc, s71, v108
	v_cvt_pk_bf16_f32 v80, v80, v81
	v_cvt_pk_bf16_f32 v81, v82, v83
	v_cvt_pk_bf16_f32 v82, v84, v85
	v_cvt_pk_bf16_f32 v83, v86, v87
	v_cvt_pk_bf16_f32 v84, v172, v173
	v_cvt_pk_bf16_f32 v85, v174, v175
	v_cvt_pk_bf16_f32 v86, v176, v177
	v_cvt_pk_bf16_f32 v87, v178, v179
	v_cvt_pk_bf16_f32 v52, v52, v53
	v_cvt_pk_bf16_f32 v53, v54, v55
	v_cvt_pk_bf16_f32 v54, v56, v57
	v_cvt_pk_bf16_f32 v55, v58, v59
	v_cvt_pk_bf16_f32 v56, v180, v181
	v_cvt_pk_bf16_f32 v57, v182, v183
	v_cvt_pk_bf16_f32 v58, v190, v191
	v_cvt_pk_bf16_f32 v59, v192, v193
	v_cvt_pk_bf16_f32 v88, v88, v89
	v_cvt_pk_bf16_f32 v89, v90, v91
	v_cvt_pk_bf16_f32 v90, v132, v133
	v_cvt_pk_bf16_f32 v91, v134, v135
	v_cvt_pk_bf16_f32 v100, v194, v195
	v_cvt_pk_bf16_f32 v101, v196, v197
	v_cvt_pk_bf16_f32 v102, v198, v199
	v_cvt_pk_bf16_f32 v103, v200, v201
	v_cvt_pk_bf16_f32 v104, v136, v137
	v_cvt_pk_bf16_f32 v105, v138, v139
	v_cvt_pk_bf16_f32 v106, v144, v145
	v_cvt_pk_bf16_f32 v107, v146, v147
	global_store_dwordx4 v[94:95], v[60:63], off
	global_store_dwordx4 v[92:93], v[64:67], off offset:256
	global_store_dwordx4 v[98:99], v[68:71], off
	global_store_dwordx4 v[96:97], v[72:75], off offset:256
	global_store_dwordx4 v[112:113], v[76:79], off
	global_store_dwordx4 v[110:111], v[80:83], off offset:256
	global_store_dwordx4 v[116:117], v[84:87], off
	global_store_dwordx4 v[114:115], v[52:55], off offset:256
	global_store_dwordx4 v[120:121], v[56:59], off
	global_store_dwordx4 v[118:119], v[88:91], off offset:256
	global_store_dwordx4 v[124:125], v[100:103], off
	global_store_dwordx4 v[122:123], v[104:107], off offset:256
	v_addc_co_u32_e32 v109, vcc, 0, v109, vcc
	global_store_dwordx4 v[126:127], v[48:51], off offset:256
	global_store_dwordx4 v[108:109], v[44:47], off
	s_cbranch_scc1 .LBB0_553
	s_waitcnt vmcnt(0)
	s_cmpk_gt_u32 s2, 0xff
	s_cbranch_scc1 .LBB0_556
	s_barrier

.LBB0_562:
	s_add_u32 s40, s6, s0
	ds_read_b128 v[112:115], v211
	ds_read_b128 v[116:119], v211 offset:1024
	ds_read_b128 v[128:131], v211 offset:2048
	ds_read_b128 v[132:135], v211 offset:3072
	s_addc_u32 s41, s7, s1
	s_add_u32 s40, s40, 0x10000100
	s_addc_u32 s41, s41, 0
	s_add_u32 s65, s62, s0
	s_addc_u32 s66, s63, s1
	s_cmpk_eq_i32 s0, 0x700
	s_cselect_b32 s43, s15, s41
	s_cselect_b32 s42, s14, s40
	s_cselect_b32 s41, s60, s66
	s_cselect_b32 s40, s61, s65
	v_lshl_add_u64 v[176:177], v[198:199], 0, s[0:1]
	s_add_i32 m0, s49, 0xc000
	ds_read_b128 v[144:147], v212
	ds_read_b128 v[148:151], v212 offset:1024
	ds_read_b128 v[152:155], v212 offset:2048
	ds_read_b128 v[156:159], v212 offset:3072
	ds_read_b128 v[160:163], v212 offset:4096
	ds_read_b128 v[164:167], v212 offset:5120
	ds_read_b128 v[168:171], v212 offset:6144
	ds_read_b128 v[172:175], v212 offset:7168
	global_load_lds_dwordx4 v[176:177], off
	v_lshl_add_u64 v[176:177], v[200:201], 0, s[0:1]
	s_add_i32 m0, s49, 0xe000
	s_nop 0
	global_load_lds_dwordx4 v[176:177], off
	s_waitcnt lgkmcnt(8)
	s_barrier
	s_waitcnt lgkmcnt(0)
	s_waitcnt lgkmcnt(0)
	v_mfma_f32_16x16x32_bf16 v[140:143], v[112:115], v[144:147], v[140:143]
	v_mfma_f32_16x16x32_bf16 v[136:139], v[128:131], v[144:147], v[136:139]
	v_mfma_f32_16x16x32_bf16 v[108:111], v[112:115], v[152:155], v[108:111]
	v_mfma_f32_16x16x32_bf16 v[104:107], v[128:131], v[152:155], v[104:107]
	v_mfma_f32_16x16x32_bf16 v[92:95], v[112:115], v[160:163], v[92:95]
	v_mfma_f32_16x16x32_bf16 v[88:91], v[128:131], v[160:163], v[88:91]
	v_mfma_f32_16x16x32_bf16 v[76:79], v[112:115], v[168:171], v[76:79]
	v_mfma_f32_16x16x32_bf16 v[72:75], v[128:131], v[168:171], v[72:75]
	v_mfma_f32_16x16x32_bf16 v[140:143], v[116:119], v[148:151], v[140:143]
	v_mfma_f32_16x16x32_bf16 v[136:139], v[132:135], v[148:151], v[136:139]
	v_mfma_f32_16x16x32_bf16 v[108:111], v[116:119], v[156:159], v[108:111]
	v_mfma_f32_16x16x32_bf16 v[104:107], v[132:135], v[156:159], v[104:107]
	v_mfma_f32_16x16x32_bf16 v[92:95], v[116:119], v[164:167], v[92:95]
	v_mfma_f32_16x16x32_bf16 v[88:91], v[132:135], v[164:167], v[88:91]
	v_mfma_f32_16x16x32_bf16 v[76:79], v[116:119], v[172:175], v[76:79]
	v_mfma_f32_16x16x32_bf16 v[72:75], v[132:135], v[172:175], v[72:75]
	s_barrier
	s_add_i32 s65, s45, s3
	v_lshl_add_u64 v[206:207], s[40:41], 0, v[194:195]
	s_mov_b32 m0, s65
	ds_read_b128 v[176:179], v213
	ds_read_b128 v[180:183], v213 offset:1024
	ds_read_b128 v[202:205], v213 offset:2048
	ds_read_b128 v[216:219], v213 offset:3072
	global_load_lds_dwordx4 v[206:207], off
	v_lshl_add_u64 v[220:221], s[40:41], 0, v[190:191]
	s_add_i32 m0, s65, 0x2000
	s_nop 0
	global_load_lds_dwordx4 v[220:221], off
	s_barrier
	s_waitcnt lgkmcnt(0)
	s_waitcnt lgkmcnt(0)
	v_mfma_f32_16x16x32_bf16 v[124:127], v[176:179], v[144:147], v[124:127]
	v_mfma_f32_16x16x32_bf16 v[120:123], v[202:205], v[144:147], v[120:123]
	v_mfma_f32_16x16x32_bf16 v[100:103], v[176:179], v[152:155], v[100:103]
	v_mfma_f32_16x16x32_bf16 v[96:99], v[202:205], v[152:155], v[96:99]
	v_mfma_f32_16x16x32_bf16 v[84:87], v[176:179], v[160:163], v[84:87]
	v_mfma_f32_16x16x32_bf16 v[80:83], v[202:205], v[160:163], v[80:83]
	v_mfma_f32_16x16x32_bf16 v[68:71], v[176:179], v[168:171], v[68:71]
	v_mfma_f32_16x16x32_bf16 v[64:67], v[202:205], v[168:171], v[64:67]
	v_mfma_f32_16x16x32_bf16 v[124:127], v[180:183], v[148:151], v[124:127]
	v_mfma_f32_16x16x32_bf16 v[120:123], v[216:219], v[148:151], v[120:123]
	v_mfma_f32_16x16x32_bf16 v[100:103], v[180:183], v[156:159], v[100:103]
	v_mfma_f32_16x16x32_bf16 v[96:99], v[216:219], v[156:159], v[96:99]
	v_mfma_f32_16x16x32_bf16 v[84:87], v[180:183], v[164:167], v[84:87]
	v_mfma_f32_16x16x32_bf16 v[80:83], v[216:219], v[164:167], v[80:83]
	v_mfma_f32_16x16x32_bf16 v[68:71], v[180:183], v[172:175], v[68:71]
	v_mfma_f32_16x16x32_bf16 v[64:67], v[216:219], v[172:175], v[64:67]
	s_mov_b32 m0, s49
	v_lshl_add_u64 v[222:223], s[42:43], 0, v[196:197]
	s_barrier
	ds_read_b128 v[144:147], v212 offset:16384
	ds_read_b128 v[148:151], v212 offset:17408
	ds_read_b128 v[152:155], v212 offset:18432
	ds_read_b128 v[156:159], v212 offset:19456
	ds_read_b128 v[160:163], v212 offset:20480
	ds_read_b128 v[164:167], v212 offset:21504
	ds_read_b128 v[168:171], v212 offset:22528
	ds_read_b128 v[172:175], v212 offset:23552
	global_load_lds_dwordx4 v[222:223], off
	v_lshl_add_u64 v[224:225], s[42:43], 0, v[192:193]
	s_mov_b32 m0, s50
	s_nop 0
	global_load_lds_dwordx4 v[224:225], off
	s_barrier
	s_waitcnt lgkmcnt(0)
	s_waitcnt lgkmcnt(0)
	v_mfma_f32_16x16x32_bf16 v[60:63], v[112:115], v[144:147], v[60:63]
	v_mfma_f32_16x16x32_bf16 v[56:59], v[128:131], v[144:147], v[56:59]
	v_mfma_f32_16x16x32_bf16 v[44:47], v[112:115], v[152:155], v[44:47]
	v_mfma_f32_16x16x32_bf16 v[40:43], v[128:131], v[152:155], v[40:43]
	v_mfma_f32_16x16x32_bf16 v[28:31], v[112:115], v[160:163], v[28:31]
	v_mfma_f32_16x16x32_bf16 v[24:27], v[128:131], v[160:163], v[24:27]
	v_mfma_f32_16x16x32_bf16 v[12:15], v[112:115], v[168:171], v[12:15]
	v_mfma_f32_16x16x32_bf16 v[8:11], v[128:131], v[168:171], v[8:11]
	v_mfma_f32_16x16x32_bf16 v[60:63], v[116:119], v[148:151], v[60:63]
	v_mfma_f32_16x16x32_bf16 v[56:59], v[132:135], v[148:151], v[56:59]
	v_mfma_f32_16x16x32_bf16 v[44:47], v[116:119], v[156:159], v[44:47]
	v_mfma_f32_16x16x32_bf16 v[40:43], v[132:135], v[156:159], v[40:43]
	v_mfma_f32_16x16x32_bf16 v[28:31], v[116:119], v[164:167], v[28:31]
	v_mfma_f32_16x16x32_bf16 v[24:27], v[132:135], v[164:167], v[24:27]
	v_mfma_f32_16x16x32_bf16 v[12:15], v[116:119], v[172:175], v[12:15]
	v_mfma_f32_16x16x32_bf16 v[8:11], v[132:135], v[172:175], v[8:11]
	s_barrier
	s_add_u32 s66, s40, 0x40000
	s_addc_u32 s67, s41, 0
	s_add_i32 s65, s46, s3
	v_lshl_add_u64 v[112:113], s[66:67], 0, v[194:195]
	s_mov_b32 m0, s65
	s_nop 0
	global_load_lds_dwordx4 v[112:113], off
	v_lshl_add_u64 v[112:113], s[66:67], 0, v[190:191]
	s_add_i32 m0, s65, 0x2000
	s_nop 0
	global_load_lds_dwordx4 v[112:113], off
	s_waitcnt vmcnt(6)
	s_barrier
	v_mfma_f32_16x16x32_bf16 v[52:55], v[176:179], v[144:147], v[52:55]
	v_mfma_f32_16x16x32_bf16 v[48:51], v[202:205], v[144:147], v[48:51]
	v_mfma_f32_16x16x32_bf16 v[36:39], v[176:179], v[152:155], v[36:39]
	v_mfma_f32_16x16x32_bf16 v[32:35], v[202:205], v[152:155], v[32:35]
	v_mfma_f32_16x16x32_bf16 v[20:23], v[176:179], v[160:163], v[20:23]
	v_mfma_f32_16x16x32_bf16 v[16:19], v[202:205], v[160:163], v[16:19]
	v_mfma_f32_16x16x32_bf16 v[4:7], v[176:179], v[168:171], v[4:7]
	v_mfma_f32_16x16x32_bf16 v[0:3], v[202:205], v[168:171], v[0:3]
	v_mfma_f32_16x16x32_bf16 v[52:55], v[180:183], v[148:151], v[52:55]
	v_mfma_f32_16x16x32_bf16 v[48:51], v[216:219], v[148:151], v[48:51]
	v_mfma_f32_16x16x32_bf16 v[36:39], v[180:183], v[156:159], v[36:39]
	v_mfma_f32_16x16x32_bf16 v[32:35], v[216:219], v[156:159], v[32:35]
	v_mfma_f32_16x16x32_bf16 v[20:23], v[180:183], v[164:167], v[20:23]
	v_mfma_f32_16x16x32_bf16 v[16:19], v[216:219], v[164:167], v[16:19]
	v_mfma_f32_16x16x32_bf16 v[4:7], v[180:183], v[172:175], v[4:7]
	v_mfma_f32_16x16x32_bf16 v[0:3], v[216:219], v[172:175], v[0:3]
	v_add_u32_e32 v132, s47, v210
	s_barrier
	ds_read_b128 v[112:115], v132
	ds_read_b128 v[116:119], v132 offset:1024
	ds_read_b128 v[128:131], v132 offset:2048
	ds_read_b128 v[132:135], v132 offset:3072
	s_add_u32 s42, s42, 0x40000
	s_addc_u32 s43, s43, 0
	s_mov_b32 m0, s51
	v_lshl_add_u64 v[176:177], s[42:43], 0, v[196:197]
	ds_read_b128 v[144:147], v212 offset:32768
	ds_read_b128 v[148:151], v212 offset:33792
	ds_read_b128 v[152:155], v212 offset:34816
	ds_read_b128 v[156:159], v212 offset:35840
	ds_read_b128 v[160:163], v212 offset:36864
	ds_read_b128 v[164:167], v212 offset:37888
	ds_read_b128 v[168:171], v212 offset:38912
	ds_read_b128 v[172:175], v212 offset:39936
	global_load_lds_dwordx4 v[176:177], off
	v_lshl_add_u64 v[176:177], s[42:43], 0, v[192:193]
	s_mov_b32 m0, s52
	s_nop 0
	global_load_lds_dwordx4 v[176:177], off
	s_waitcnt lgkmcnt(8)
	s_barrier
	s_waitcnt lgkmcnt(0)
	s_waitcnt lgkmcnt(0)
	v_mfma_f32_16x16x32_bf16 v[140:143], v[112:115], v[144:147], v[140:143]
	v_mfma_f32_16x16x32_bf16 v[136:139], v[128:131], v[144:147], v[136:139]
	v_mfma_f32_16x16x32_bf16 v[108:111], v[112:115], v[152:155], v[108:111]
	v_mfma_f32_16x16x32_bf16 v[104:107], v[128:131], v[152:155], v[104:107]
	v_mfma_f32_16x16x32_bf16 v[92:95], v[112:115], v[160:163], v[92:95]
	v_mfma_f32_16x16x32_bf16 v[88:91], v[128:131], v[160:163], v[88:91]
	v_mfma_f32_16x16x32_bf16 v[76:79], v[112:115], v[168:171], v[76:79]
	v_mfma_f32_16x16x32_bf16 v[72:75], v[128:131], v[168:171], v[72:75]
	v_mfma_f32_16x16x32_bf16 v[140:143], v[116:119], v[148:151], v[140:143]
	v_mfma_f32_16x16x32_bf16 v[136:139], v[132:135], v[148:151], v[136:139]
	v_mfma_f32_16x16x32_bf16 v[108:111], v[116:119], v[156:159], v[108:111]
	v_mfma_f32_16x16x32_bf16 v[104:107], v[132:135], v[156:159], v[104:107]
	v_mfma_f32_16x16x32_bf16 v[92:95], v[116:119], v[164:167], v[92:95]
	v_mfma_f32_16x16x32_bf16 v[88:91], v[132:135], v[164:167], v[88:91]
	v_mfma_f32_16x16x32_bf16 v[76:79], v[116:119], v[172:175], v[76:79]
	v_mfma_f32_16x16x32_bf16 v[72:75], v[132:135], v[172:175], v[72:75]
	s_barrier
	s_add_i32 s42, s47, s3
	v_add_u32_e32 v215, s48, v210
	v_lshl_add_u64 v[206:207], v[206:207], 0, s[20:21]
	s_mov_b32 m0, s42
	ds_read_b128 v[176:179], v215
	ds_read_b128 v[180:183], v215 offset:1024
	ds_read_b128 v[202:205], v215 offset:2048
	ds_read_b128 v[216:219], v215 offset:3072
	global_load_lds_dwordx4 v[206:207], off
	v_lshl_add_u64 v[206:207], v[220:221], 0, s[20:21]
	s_add_i32 m0, s42, 0x2000
	s_nop 0
	global_load_lds_dwordx4 v[206:207], off
	s_barrier
	s_waitcnt lgkmcnt(0)
	s_waitcnt lgkmcnt(0)
	v_mfma_f32_16x16x32_bf16 v[124:127], v[176:179], v[144:147], v[124:127]
	v_mfma_f32_16x16x32_bf16 v[120:123], v[202:205], v[144:147], v[120:123]
	v_mfma_f32_16x16x32_bf16 v[100:103], v[176:179], v[152:155], v[100:103]
	v_mfma_f32_16x16x32_bf16 v[96:99], v[202:205], v[152:155], v[96:99]
	v_mfma_f32_16x16x32_bf16 v[84:87], v[176:179], v[160:163], v[84:87]
	v_mfma_f32_16x16x32_bf16 v[80:83], v[202:205], v[160:163], v[80:83]
	v_mfma_f32_16x16x32_bf16 v[68:71], v[176:179], v[168:171], v[68:71]
	v_mfma_f32_16x16x32_bf16 v[64:67], v[202:205], v[168:171], v[64:67]
	v_mfma_f32_16x16x32_bf16 v[124:127], v[180:183], v[148:151], v[124:127]
	v_mfma_f32_16x16x32_bf16 v[120:123], v[216:219], v[148:151], v[120:123]
	v_mfma_f32_16x16x32_bf16 v[100:103], v[180:183], v[156:159], v[100:103]
	v_mfma_f32_16x16x32_bf16 v[96:99], v[216:219], v[156:159], v[96:99]
	v_mfma_f32_16x16x32_bf16 v[84:87], v[180:183], v[164:167], v[84:87]
	v_mfma_f32_16x16x32_bf16 v[80:83], v[216:219], v[164:167], v[80:83]
	v_mfma_f32_16x16x32_bf16 v[68:71], v[180:183], v[172:175], v[68:71]
	v_mfma_f32_16x16x32_bf16 v[64:67], v[216:219], v[172:175], v[64:67]
	s_mov_b32 m0, s56
	v_lshl_add_u64 v[206:207], v[222:223], 0, s[20:21]
	s_barrier
	ds_read_b128 v[144:147], v212 offset:49152
	ds_read_b128 v[148:151], v212 offset:50176
	ds_read_b128 v[152:155], v212 offset:51200
	ds_read_b128 v[156:159], v212 offset:52224
	ds_read_b128 v[160:163], v212 offset:53248
	ds_read_b128 v[164:167], v212 offset:54272
	ds_read_b128 v[168:171], v212 offset:55296
	ds_read_b128 v[172:175], v212 offset:56320
	global_load_lds_dwordx4 v[206:207], off
	v_lshl_add_u64 v[206:207], v[224:225], 0, s[20:21]
	s_mov_b32 m0, s57
	s_nop 0
	global_load_lds_dwordx4 v[206:207], off
	s_barrier
	s_waitcnt lgkmcnt(0)
	s_waitcnt lgkmcnt(0)
	v_mfma_f32_16x16x32_bf16 v[60:63], v[112:115], v[144:147], v[60:63]
	v_mfma_f32_16x16x32_bf16 v[56:59], v[128:131], v[144:147], v[56:59]
	v_mfma_f32_16x16x32_bf16 v[44:47], v[112:115], v[152:155], v[44:47]
	v_mfma_f32_16x16x32_bf16 v[40:43], v[128:131], v[152:155], v[40:43]
	v_mfma_f32_16x16x32_bf16 v[28:31], v[112:115], v[160:163], v[28:31]
	v_mfma_f32_16x16x32_bf16 v[24:27], v[128:131], v[160:163], v[24:27]
	v_mfma_f32_16x16x32_bf16 v[12:15], v[112:115], v[168:171], v[12:15]
	v_mfma_f32_16x16x32_bf16 v[8:11], v[128:131], v[168:171], v[8:11]
	v_mfma_f32_16x16x32_bf16 v[60:63], v[116:119], v[148:151], v[60:63]
	v_mfma_f32_16x16x32_bf16 v[56:59], v[132:135], v[148:151], v[56:59]
	v_mfma_f32_16x16x32_bf16 v[44:47], v[116:119], v[156:159], v[44:47]
	v_mfma_f32_16x16x32_bf16 v[40:43], v[132:135], v[156:159], v[40:43]
	v_mfma_f32_16x16x32_bf16 v[28:31], v[116:119], v[164:167], v[28:31]
	v_mfma_f32_16x16x32_bf16 v[24:27], v[132:135], v[164:167], v[24:27]
	v_mfma_f32_16x16x32_bf16 v[12:15], v[116:119], v[172:175], v[12:15]
	v_mfma_f32_16x16x32_bf16 v[8:11], v[132:135], v[172:175], v[8:11]
	s_barrier
	s_add_u32 s40, s40, 0x40080
	s_addc_u32 s41, s41, 0
	s_add_i32 s42, s48, s3
	v_lshl_add_u64 v[112:113], s[40:41], 0, v[194:195]
	s_mov_b32 m0, s42
	s_nop 0
	global_load_lds_dwordx4 v[112:113], off
	v_lshl_add_u64 v[112:113], s[40:41], 0, v[190:191]
	s_add_i32 m0, s42, 0x2000
	s_nop 0
	global_load_lds_dwordx4 v[112:113], off
	s_waitcnt vmcnt(6)
	s_barrier
	v_mfma_f32_16x16x32_bf16 v[52:55], v[176:179], v[144:147], v[52:55]
	v_mfma_f32_16x16x32_bf16 v[48:51], v[202:205], v[144:147], v[48:51]
	v_mfma_f32_16x16x32_bf16 v[36:39], v[176:179], v[152:155], v[36:39]
	v_mfma_f32_16x16x32_bf16 v[32:35], v[202:205], v[152:155], v[32:35]
	v_mfma_f32_16x16x32_bf16 v[20:23], v[176:179], v[160:163], v[20:23]
	v_mfma_f32_16x16x32_bf16 v[16:19], v[202:205], v[160:163], v[16:19]
	v_mfma_f32_16x16x32_bf16 v[4:7], v[176:179], v[168:171], v[4:7]
	v_mfma_f32_16x16x32_bf16 v[0:3], v[202:205], v[168:171], v[0:3]
	v_mfma_f32_16x16x32_bf16 v[52:55], v[180:183], v[148:151], v[52:55]
	v_mfma_f32_16x16x32_bf16 v[48:51], v[216:219], v[148:151], v[48:51]
	v_mfma_f32_16x16x32_bf16 v[36:39], v[180:183], v[156:159], v[36:39]
	v_mfma_f32_16x16x32_bf16 v[32:35], v[216:219], v[156:159], v[32:35]
	v_mfma_f32_16x16x32_bf16 v[20:23], v[180:183], v[164:167], v[20:23]
	v_mfma_f32_16x16x32_bf16 v[16:19], v[216:219], v[164:167], v[16:19]
	v_mfma_f32_16x16x32_bf16 v[4:7], v[180:183], v[172:175], v[4:7]
	v_mfma_f32_16x16x32_bf16 v[0:3], v[216:219], v[172:175], v[0:3]
	s_add_i32 s64, s64, 2
	s_add_u32 s0, s0, 0x100
	s_addc_u32 s1, s1, 0
	s_cmp_gt_u32 s64, 13
	s_barrier
	s_cbranch_scc0 .LBB0_562
	v_mov_b32_e32 v112, v208
	v_mov_b32_e32 v118, v209
	s_lshl_b32 s0, s59, 8
	v_add_u32_e32 v215, s54, v112
	v_add_u32_e32 v204, s44, v215
	s_or_b32 s0, s0, s55
	v_lshl_add_u32 v202, v118, 3, s0
	v_ashrrev_i32_e32 v205, 31, v204
	v_ashrrev_i32_e32 v203, 31, v202
	v_lshlrev_b64 v[112:113], 10, v[204:205]
	v_lshl_add_u64 v[112:113], v[112:113], 0, v[202:203]
	v_lshlrev_b64 v[112:113], 1, v[112:113]
	v_lshl_add_u64 v[114:115], s[24:25], 0, v[112:113]
	global_load_dwordx4 v[218:221], v[114:115], off
	v_lshl_add_u64 v[116:117], s[26:27], 0, v[112:113]
	global_load_dwordx4 v[222:225], v[116:117], off
	v_lshl_add_u32 v217, v215, 2, 0
	v_add_u32_e32 v216, 0x20000, v217
	ds_read_b32 v130, v216
	global_load_dwordx4 v[176:179], v[116:117], off offset:256
	global_load_dwordx4 v[180:183], v[114:115], off offset:256
	v_cmp_eq_u32_e32 vcc, 0, v118
	v_lshl_add_u64 v[118:119], v[112:113], 0, s[8:9]
	v_lshl_add_u64 v[128:129], v[112:113], 0, s[22:23]
	v_lshl_add_u64 v[114:115], s[26:27], 0, v[118:119]
	v_lshl_add_u64 v[112:113], v[112:113], 0, s[28:29]
	v_lshl_add_u64 v[116:117], s[24:25], 0, v[118:119]
	v_lshl_add_u64 v[118:119], s[26:27], 0, v[128:129]
	v_lshl_add_u64 v[128:129], s[24:25], 0, v[128:129]
	global_load_dwordx4 v[168:171], v[114:115], off
	global_load_dwordx4 v[160:163], v[114:115], off offset:256
	global_load_dwordx4 v[172:175], v[116:117], off
	global_load_dwordx4 v[164:167], v[116:117], off offset:256
	global_load_dwordx4 v[152:155], v[118:119], off
	global_load_dwordx4 v[144:147], v[118:119], off offset:256
	global_load_dwordx4 v[156:159], v[128:129], off
	global_load_dwordx4 v[148:151], v[128:129], off offset:256
	v_lshl_add_u64 v[132:133], s[26:27], 0, v[112:113]
	v_lshl_add_u64 v[226:227], s[24:25], 0, v[112:113]
	s_waitcnt lgkmcnt(0)
	v_fmamk_f32 v112, v130, 0x3a800000, v214
	v_mul_f32_e32 v113, 0x4b800000, v112
	v_cmp_gt_f32_e64 s[0:1], s58, v112
	v_lshlrev_b64 v[206:207], 11, v[204:205]
	s_waitcnt vmcnt(0)
	v_and_b32_e32 v229, 0xffff0000, v220
	v_cndmask_b32_e64 v112, v112, v113, s[0:1]
	v_rsq_f32_e32 v228, v112
	global_load_dwordx4 v[128:131], v[132:133], off
	global_load_dwordx4 v[112:115], v[132:133], off offset:256
	s_nop 0
	global_load_dwordx4 v[132:135], v[226:227], off
	global_load_dwordx4 v[116:119], v[226:227], off offset:256
	v_and_b32_e32 v227, 0xffff0000, v222
	v_lshlrev_b32_e32 v230, 16, v224
	v_mul_f32_e32 v226, 0x45800000, v228
	v_cndmask_b32_e64 v232, v228, v226, s[0:1]
	v_mul_f32_e32 v140, v140, v232
	v_mul_f32_e32 v136, v136, v232
	v_mul_f32_e32 v141, v141, v232
	v_mul_f32_e32 v142, v142, v232
	v_mul_f32_e32 v140, 0xbfb8aa3b, v140
	v_mul_f32_e32 v136, 0xbfb8aa3b, v136
	v_mul_f32_e32 v137, v137, v232
	v_mul_f32_e32 v141, 0xbfb8aa3b, v141
	v_mul_f32_e32 v142, 0xbfb8aa3b, v142
	v_exp_f32_e32 v140, v140
	v_exp_f32_e32 v136, v136
	v_mul_f32_e32 v137, 0xbfb8aa3b, v137
	v_exp_f32_e32 v141, v141
	v_exp_f32_e32 v142, v142
	v_exp_f32_e32 v137, v137
	v_mul_f32_e32 v143, v143, v232
	v_mul_f32_e32 v138, v138, v232
	v_mul_f32_e32 v233, 0xbfb8aa3b, v143
	v_add_f32_e32 v140, 1.0, v140
	v_add_f32_e32 v143, 1.0, v136
	v_mul_f32_e32 v139, v139, v232
	v_mul_f32_e32 v138, 0xbfb8aa3b, v138
	v_add_f32_e32 v141, 1.0, v141
	v_add_f32_e32 v234, 1.0, v142
	v_rcp_f32_e32 v136, v140
	v_rcp_f32_e32 v140, v143
	v_lshlrev_b32_e32 v142, 16, v218
	v_and_b32_e32 v143, 0xffff0000, v218
	v_exp_f32_e32 v218, v233
	v_mul_f32_e32 v139, 0xbfb8aa3b, v139
	v_exp_f32_e32 v138, v138
	v_add_f32_e32 v226, 1.0, v137
	v_rcp_f32_e32 v137, v141
	v_exp_f32_e32 v139, v139
	v_mul_f32_e32 v124, v124, v232
	v_mul_f32_e32 v125, v125, v232
	v_mul_f32_e32 v124, 0xbfb8aa3b, v124
	v_mul_f32_e32 v120, v120, v232
	v_mul_f32_e32 v125, 0xbfb8aa3b, v125
	v_mul_f32_e32 v121, v121, v232
	v_rcp_f32_e32 v141, v226
	v_lshlrev_b32_e32 v226, 16, v222
	v_add_f32_e32 v218, 1.0, v218
	v_exp_f32_e32 v124, v124
	v_mul_f32_e32 v120, 0xbfb8aa3b, v120
	v_exp_f32_e32 v125, v125
	v_mul_f32_e32 v121, 0xbfb8aa3b, v121
	v_mul_f32_e32 v126, v126, v232
	v_mul_f32_e32 v127, v127, v232
	v_pk_fma_f32 v[136:137], v[136:137], v[142:143], v[226:227]
	v_rcp_f32_e32 v226, v234
	v_add_f32_e32 v138, 1.0, v138
	v_rcp_f32_e32 v227, v218
	v_add_f32_e32 v139, 1.0, v139
	v_exp_f32_e32 v120, v120
	v_exp_f32_e32 v121, v121
	v_mul_f32_e32 v126, 0xbfb8aa3b, v126
	v_mul_f32_e32 v122, v122, v232
	v_mul_f32_e32 v127, 0xbfb8aa3b, v127
	v_mul_f32_e32 v123, v123, v232
	v_rcp_f32_e32 v138, v138
	v_rcp_f32_e32 v139, v139
	v_exp_f32_e32 v126, v126
	v_mul_f32_e32 v122, 0xbfb8aa3b, v122
	v_exp_f32_e32 v127, v127
	v_mul_f32_e32 v123, 0xbfb8aa3b, v123
	v_exp_f32_e32 v122, v122
	v_exp_f32_e32 v123, v123
	v_lshlrev_b32_e32 v218, 16, v219
	v_and_b32_e32 v219, 0xffff0000, v219
	v_lshlrev_b32_e32 v222, 16, v223
	v_and_b32_e32 v223, 0xffff0000, v223
	v_add_f32_e32 v124, 1.0, v124
	v_add_f32_e32 v125, 1.0, v125
	v_lshlrev_b32_e32 v228, 16, v220
	v_and_b32_e32 v231, 0xffff0000, v224
	v_pk_fma_f32 v[218:219], v[226:227], v[218:219], v[222:223]
	v_lshlrev_b32_e32 v220, 16, v221
	v_and_b32_e32 v221, 0xffff0000, v221
	v_lshlrev_b32_e32 v222, 16, v225
	v_and_b32_e32 v223, 0xffff0000, v225
	v_rcp_f32_e32 v124, v124
	v_add_f32_e32 v120, 1.0, v120
	v_rcp_f32_e32 v125, v125
	v_add_f32_e32 v121, 1.0, v121
	v_pk_fma_f32 v[140:141], v[140:141], v[228:229], v[230:231]
	v_pk_fma_f32 v[220:221], v[138:139], v[220:221], v[222:223]
	v_rcp_f32_e32 v120, v120
	v_rcp_f32_e32 v121, v121
	v_add_f32_e32 v126, 1.0, v126
	v_add_f32_e32 v127, 1.0, v127
	v_pk_mul_f32 v[142:143], v[140:141], v[140:141]
	v_pk_mul_f32 v[138:139], v[220:221], v[220:221]
	v_rcp_f32_e32 v126, v126
	v_add_f32_e32 v122, 1.0, v122
	v_rcp_f32_e32 v127, v127
	v_add_f32_e32 v123, 1.0, v123
	v_pk_fma_f32 v[142:143], v[136:137], v[136:137], v[142:143]
	v_pk_fma_f32 v[222:223], v[218:219], v[218:219], v[138:139]
	v_cvt_pk_bf16_f32 v136, v136, v137
	v_cvt_pk_bf16_f32 v137, v218, v219
	v_cvt_pk_bf16_f32 v138, v140, v141
	v_lshlrev_b32_e32 v140, 16, v180
	v_and_b32_e32 v141, 0xffff0000, v180
	v_lshlrev_b32_e32 v218, 16, v176
	v_and_b32_e32 v219, 0xffff0000, v176
	v_rcp_f32_e32 v122, v122
	v_rcp_f32_e32 v123, v123
	v_pk_fma_f32 v[124:125], v[124:125], v[140:141], v[218:219]
	v_lshlrev_b32_e32 v140, 16, v182
	v_and_b32_e32 v141, 0xffff0000, v182
	v_lshlrev_b32_e32 v218, 16, v178
	v_and_b32_e32 v219, 0xffff0000, v178
	v_pk_fma_f32 v[140:141], v[120:121], v[140:141], v[218:219]
	v_lshlrev_b32_e32 v180, 16, v181
	v_and_b32_e32 v181, 0xffff0000, v181
	v_lshlrev_b32_e32 v176, 16, v177
	v_and_b32_e32 v177, 0xffff0000, v177
	v_add_f32_e32 v142, v142, v143
	v_pk_mul_f32 v[120:121], v[140:141], v[140:141]
	v_pk_fma_f32 v[126:127], v[126:127], v[180:181], v[176:177]
	v_lshlrev_b32_e32 v176, 16, v183
	v_and_b32_e32 v177, 0xffff0000, v183
	v_lshlrev_b32_e32 v178, 16, v179
	v_and_b32_e32 v179, 0xffff0000, v179
	v_add_f32_e32 v142, v222, v142
	v_pk_fma_f32 v[120:121], v[124:125], v[124:125], v[120:121]
	v_pk_fma_f32 v[176:177], v[122:123], v[176:177], v[178:179]
	v_add_f32_e32 v142, v223, v142
	v_pk_mul_f32 v[122:123], v[176:177], v[176:177]
	v_add_f32_e32 v120, v120, v142
	v_pk_fma_f32 v[122:123], v[126:127], v[126:127], v[122:123]
	v_add_f32_e32 v120, v121, v120
	v_add_f32_e32 v120, v122, v120
	v_add_f32_e32 v123, v123, v120
	ds_bpermute_b32 v178, v187, v123
	v_lshl_add_u64 v[120:121], s[18:19], 0, v[206:207]
	v_lshl_add_u64 v[142:143], v[202:203], 1, v[120:121]
	v_cvt_pk_bf16_f32 v139, v220, v221
	v_cvt_pk_bf16_f32 v122, v124, v125
	s_waitcnt lgkmcnt(0)
	v_add_f32_e32 v120, v123, v178
	ds_bpermute_b32 v121, v189, v120
	v_cvt_pk_bf16_f32 v123, v126, v127
	v_cvt_pk_bf16_f32 v124, v140, v141
	v_cvt_pk_bf16_f32 v125, v176, v177
	global_store_dwordx4 v[142:143], v[136:139], off
	global_store_dwordx4 v[142:143], v[122:125], off offset:256
	s_and_saveexec_b64 s[0:1], vcc
	s_cbranch_execz .LBB0_565
	s_waitcnt lgkmcnt(0)
	v_add_f32_e32 v120, v120, v121
	v_add_u32_e32 v121, 0x20400, v217
	ds_add_f32 v121, v120
